# baseline (speedup 1.0000x reference)
; #define PG8_STAGE(bufoff, gbase, voff) do { _Pragma("unroll") for (int _i = 0; _i < 2; ++_i) \
;         __builtin_amdgcn_global_load_lds((const unsigned*)((const char*)(gbase) + (voff)[_i]), (LAS unsigned*)(lds + (bufoff) + ldsw + _i * 8192), 16, 0, 0); } while (0)
; #define PG8_LDA(dst, b, h) do { _Pragma("unroll") for (int m = 0; m < 4; ++m) _Pragma("unroll") for (int k = 0; k < 2; ++k) dst[m][k] = *(const LAS bf16x8*)(lds + PG8_SA(b, h) + aoff + m * 2048 + k * 1024); } while (0)
; #define PG8_LDB(dst, b, h) do { _Pragma("unroll") for (int n = 0; n < 2; ++n) _Pragma("unroll") for (int k = 0; k < 2; ++k) dst[n][k] = *(const LAS bf16x8*)(lds + PG8_SB(b, h) + boff + n * 2048 + k * 1024); } while (0)
; #define PG8_WAIT_V(n) asm volatile("s_waitcnt vmcnt(" #n ")" ::: "memory")
; #define PG8_WAIT_L(n) asm volatile("s_waitcnt lgkmcnt(" #n ")" ::: "memory")
; #define PG8_BAR __builtin_amdgcn_s_barrier()
; #define PG8_SCHED __builtin_amdgcn_sched_barrier(0)
; template <class Epi, class Sched, bool FUSED = false, bool APERM = false>
; __device__ __forceinline__ void gemm_phase(int wid_s, LAS unsigned char* lds, const Gemm g, const Sched& S, const Epi& E) {
;     ...
;             const bool last = (t == nt - 2);
;             const char* a1 = cA + (size_t)(t + 1) * kstep;
;             const char* a2 = last ? nA : cA + (size_t)(t + 2) * kstep; const char* b2 = last ? nB : cB + (size_t)(t + 2) * kstep;
;             const char* a3 = a2 + kstep; const char* b3 = b2 + kstep;
;             if (last && has_next) S.a_ready(nxt);
;             PG8_LDB(B0, 0, 0); PG8_LDB(B1, 0, 1); PG8_SCHED; PG8_LDA(At, 0, 0); PG8_STAGE(PG8_SA(1, 1), a1 + hstep, voffA);
;             PG8_WAIT_V(8); PG8_WAIT_L(0); PG8_BAR; PG8_MMA(0, 0, At, B0); PG8_MMA(0, 1, At, B1); PG8_BAR; PG8_SCHED;
;             PG8_LDA(At, 0, 1); PG8_STAGE(PG8_SB(0, 0), b2, voffB); PG8_STAGE(PG8_SB(0, 1), b2 + hstep, voffB); PG8_STAGE(PG8_SA(0, 0), a2, voffA);
.LBB0_145:
	s_add_u32 s42, s40, 0xfff80080
	s_addc_u32 s43, s41, -1
	s_add_i32 s68, 0, 0x10000
	s_cmp_eq_u32 s67, 28
	s_cselect_b32 s45, s3, s43
	s_cselect_b32 s44, s10, s42
	s_cselect_b32 s43, s25, s66
	s_cselect_b32 s42, s27, s35
	s_add_i32 s70, 0, 0x14000
	v_add_u32_e32 v144, s68, v227
	v_add_u32_e32 v160, s70, v227
	ds_read_b128 v[132:135], v144
	ds_read_b128 v[136:139], v144 offset:1024
	ds_read_b128 v[140:143], v144 offset:2048
	ds_read_b128 v[144:147], v144 offset:3072
	ds_read_b128 v[148:151], v160
	ds_read_b128 v[152:155], v160 offset:1024
	ds_read_b128 v[156:159], v160 offset:2048
	ds_read_b128 v[160:163], v160 offset:3072
	v_lshl_add_u64 v[214:215], s[40:41], 0, v[212:213]
	s_add_i32 m0, s52, 0xc000
	ds_read_b128 v[164:167], v228
	ds_read_b128 v[168:171], v228 offset:1024
	ds_read_b128 v[172:175], v228 offset:2048
	ds_read_b128 v[176:179], v228 offset:3072
	ds_read_b128 v[180:183], v228 offset:4096
	ds_read_b128 v[184:187], v228 offset:5120
	ds_read_b128 v[188:191], v228 offset:6144
	ds_read_b128 v[192:195], v228 offset:7168
	global_load_lds_dwordx4 v[214:215], off
	v_lshl_add_u64 v[214:215], s[40:41], 0, v[210:211]
	s_add_i32 m0, s52, 0xe000
	s_nop 0
	global_load_lds_dwordx4 v[214:215], off
	s_waitcnt vmcnt(8)
	s_waitcnt lgkmcnt(0)
	s_barrier
	v_mfma_f32_16x16x32_f16 v[128:131], v[132:135], v[164:167], v[128:131]
	v_mfma_f32_16x16x32_f16 v[124:127], v[140:143], v[164:167], v[124:127]
	v_mfma_f32_16x16x32_f16 v[112:115], v[132:135], v[172:175], v[112:115]
	v_mfma_f32_16x16x32_f16 v[108:111], v[140:143], v[172:175], v[108:111]
	v_mfma_f32_16x16x32_f16 v[96:99], v[132:135], v[180:183], v[96:99]
	v_mfma_f32_16x16x32_f16 v[92:95], v[140:143], v[180:183], v[92:95]
	v_mfma_f32_16x16x32_f16 v[80:83], v[132:135], v[188:191], v[80:83]
	v_mfma_f32_16x16x32_f16 v[76:79], v[140:143], v[188:191], v[76:79]
	v_mfma_f32_16x16x32_f16 v[128:131], v[136:139], v[168:171], v[128:131]
	v_mfma_f32_16x16x32_f16 v[124:127], v[144:147], v[168:171], v[124:127]
	v_mfma_f32_16x16x32_f16 v[112:115], v[136:139], v[176:179], v[112:115]
	v_mfma_f32_16x16x32_f16 v[108:111], v[144:147], v[176:179], v[108:111]
	v_mfma_f32_16x16x32_f16 v[96:99], v[136:139], v[184:187], v[96:99]
	v_mfma_f32_16x16x32_f16 v[92:95], v[144:147], v[184:187], v[92:95]
	v_mfma_f32_16x16x32_f16 v[80:83], v[136:139], v[192:195], v[80:83]
	v_mfma_f32_16x16x32_f16 v[76:79], v[144:147], v[192:195], v[76:79]
	v_mfma_f32_16x16x32_f16 v[120:123], v[148:151], v[164:167], v[120:123]
	v_mfma_f32_16x16x32_f16 v[116:119], v[156:159], v[164:167], v[116:119]
	v_mfma_f32_16x16x32_f16 v[104:107], v[148:151], v[172:175], v[104:107]
	v_mfma_f32_16x16x32_f16 v[100:103], v[156:159], v[172:175], v[100:103]
	v_mfma_f32_16x16x32_f16 v[88:91], v[148:151], v[180:183], v[88:91]
	v_mfma_f32_16x16x32_f16 v[84:87], v[156:159], v[180:183], v[84:87]
	v_mfma_f32_16x16x32_f16 v[68:71], v[148:151], v[188:191], v[68:71]
	v_mfma_f32_16x16x32_f16 v[72:75], v[156:159], v[188:191], v[72:75]
	v_mfma_f32_16x16x32_f16 v[120:123], v[152:155], v[168:171], v[120:123]
	v_mfma_f32_16x16x32_f16 v[116:119], v[160:163], v[168:171], v[116:119]
	v_mfma_f32_16x16x32_f16 v[104:107], v[152:155], v[176:179], v[104:107]
	v_mfma_f32_16x16x32_f16 v[100:103], v[160:163], v[176:179], v[100:103]
	v_mfma_f32_16x16x32_f16 v[88:91], v[152:155], v[184:187], v[88:91]
	v_mfma_f32_16x16x32_f16 v[84:87], v[160:163], v[184:187], v[84:87]
	v_mfma_f32_16x16x32_f16 v[68:71], v[152:155], v[192:195], v[68:71]
	v_mfma_f32_16x16x32_f16 v[72:75], v[160:163], v[192:195], v[72:75]
	s_barrier
	s_add_i32 s68, s68, s51
	v_lshl_add_u64 v[214:215], s[42:43], 0, v[0:1]
	s_mov_b32 m0, s68
	ds_read_b128 v[164:167], v228 offset:16384
	ds_read_b128 v[168:171], v228 offset:17408
	ds_read_b128 v[172:175], v228 offset:18432
	ds_read_b128 v[176:179], v228 offset:19456
	ds_read_b128 v[180:183], v228 offset:20480
	ds_read_b128 v[184:187], v228 offset:21504
	ds_read_b128 v[188:191], v228 offset:22528
	ds_read_b128 v[192:195], v228 offset:23552
	global_load_lds_dwordx4 v[214:215], off
	s_add_i32 m0, s68, 0x2000
	s_add_u32 s68, s42, 0x80000
	v_lshl_add_u64 v[216:217], s[42:43], 0, v[208:209]
	s_addc_u32 s69, s43, 0
	s_add_i32 s70, s70, s51
	global_load_lds_dwordx4 v[216:217], off
	v_lshl_add_u64 v[218:219], s[68:69], 0, v[0:1]
	s_mov_b32 m0, s70
	v_lshl_add_u64 v[220:221], s[44:45], 0, v[208:209]
	global_load_lds_dwordx4 v[218:219], off
	v_lshl_add_u64 v[218:219], s[68:69], 0, v[208:209]
	s_add_i32 m0, s70, 0x2000
	s_nop 0
	global_load_lds_dwordx4 v[218:219], off
	v_lshl_add_u64 v[218:219], s[44:45], 0, v[0:1]
	s_mov_b32 m0, s52
	s_nop 0
	global_load_lds_dwordx4 v[218:219], off
	s_mov_b32 m0, s53
	s_nop 0
	global_load_lds_dwordx4 v[220:221], off
	s_waitcnt vmcnt(8)
	s_waitcnt lgkmcnt(0)
	s_barrier
; #define PG8_STAGE(bufoff, gbase, voff) do { _Pragma("unroll") for (int _i = 0; _i < 2; ++_i) \
;         __builtin_amdgcn_global_load_lds((const unsigned*)((const char*)(gbase) + (voff)[_i]), (LAS unsigned*)(lds + (bufoff) + ldsw + _i * 8192), 16, 0, 0); } while (0)
; #define PG8_LDA(dst, b, h) do { _Pragma("unroll") for (int m = 0; m < 4; ++m) _Pragma("unroll") for (int k = 0; k < 2; ++k) dst[m][k] = *(const LAS bf16x8*)(lds + PG8_SA(b, h) + aoff + m * 2048 + k * 1024); } while (0)
; #define PG8_LDB(dst, b, h) do { _Pragma("unroll") for (int n = 0; n < 2; ++n) _Pragma("unroll") for (int k = 0; k < 2; ++k) dst[n][k] = *(const LAS bf16x8*)(lds + PG8_SB(b, h) + boff + n * 2048 + k * 1024); } while (0)
; #define PG8_WAIT_V(n) asm volatile("s_waitcnt vmcnt(" #n ")" ::: "memory")
; #define PG8_WAIT_L(n) asm volatile("s_waitcnt lgkmcnt(" #n ")" ::: "memory")
; #define PG8_BAR __builtin_amdgcn_s_barrier()
; #define PG8_SCHED __builtin_amdgcn_sched_barrier(0)
; template <class Epi, class Sched, bool FUSED = false, bool APERM = false>
; __device__ __forceinline__ void gemm_phase(int wid_s, LAS unsigned char* lds, const Gemm g, const Sched& S, const Epi& E) {
;     ...
;             PG8_WAIT_V(8); PG8_WAIT_L(0); PG8_BAR; PG8_MMA(1, 0, At, B0); PG8_MMA(1, 1, At, B1); PG8_BAR; PG8_SCHED;
;             PG8_LDB(B0, 1, 0); PG8_LDB(B1, 1, 1); PG8_SCHED; PG8_LDA(At, 1, 0); PG8_STAGE(PG8_SA(0, 1), a2 + hstep, voffA);
;             PG8_WAIT_V(8); PG8_WAIT_L(0); PG8_BAR; PG8_MMA(0, 0, At, B0); PG8_MMA(0, 1, At, B1); PG8_BAR; PG8_SCHED;
	v_mfma_f32_16x16x32_f16 v[64:67], v[132:135], v[164:167], v[64:67]
	v_mfma_f32_16x16x32_f16 v[60:63], v[140:143], v[164:167], v[60:63]
	v_mfma_f32_16x16x32_f16 v[48:51], v[132:135], v[172:175], v[48:51]
	v_mfma_f32_16x16x32_f16 v[44:47], v[140:143], v[172:175], v[44:47]
	v_mfma_f32_16x16x32_f16 v[32:35], v[132:135], v[180:183], v[32:35]
	v_mfma_f32_16x16x32_f16 v[28:31], v[140:143], v[180:183], v[28:31]
	v_mfma_f32_16x16x32_f16 v[12:15], v[132:135], v[188:191], v[12:15]
	v_mfma_f32_16x16x32_f16 v[16:19], v[140:143], v[188:191], v[16:19]
	v_mfma_f32_16x16x32_f16 v[64:67], v[136:139], v[168:171], v[64:67]
	v_mfma_f32_16x16x32_f16 v[60:63], v[144:147], v[168:171], v[60:63]
	v_mfma_f32_16x16x32_f16 v[48:51], v[136:139], v[176:179], v[48:51]
	v_mfma_f32_16x16x32_f16 v[44:47], v[144:147], v[176:179], v[44:47]
	v_mfma_f32_16x16x32_f16 v[32:35], v[136:139], v[184:187], v[32:35]
	v_mfma_f32_16x16x32_f16 v[28:31], v[144:147], v[184:187], v[28:31]
	v_mfma_f32_16x16x32_f16 v[12:15], v[136:139], v[192:195], v[12:15]
	v_mfma_f32_16x16x32_f16 v[16:19], v[144:147], v[192:195], v[16:19]
	v_mfma_f32_16x16x32_f16 v[56:59], v[148:151], v[164:167], v[56:59]
	v_mfma_f32_16x16x32_f16 v[52:55], v[156:159], v[164:167], v[52:55]
	v_mfma_f32_16x16x32_f16 v[40:43], v[148:151], v[172:175], v[40:43]
	v_mfma_f32_16x16x32_f16 v[36:39], v[156:159], v[172:175], v[36:39]
	v_mfma_f32_16x16x32_f16 v[24:27], v[148:151], v[180:183], v[24:27]
	v_mfma_f32_16x16x32_f16 v[20:23], v[156:159], v[180:183], v[20:23]
	v_mfma_f32_16x16x32_f16 v[4:7], v[148:151], v[188:191], v[4:7]
	v_mfma_f32_16x16x32_f16 v[8:11], v[156:159], v[188:191], v[8:11]
	v_mfma_f32_16x16x32_f16 v[56:59], v[152:155], v[168:171], v[56:59]
	v_mfma_f32_16x16x32_f16 v[52:55], v[160:163], v[168:171], v[52:55]
	v_mfma_f32_16x16x32_f16 v[40:43], v[152:155], v[176:179], v[40:43]
	v_mfma_f32_16x16x32_f16 v[36:39], v[160:163], v[176:179], v[36:39]
	v_mfma_f32_16x16x32_f16 v[24:27], v[152:155], v[184:187], v[24:27]
	v_mfma_f32_16x16x32_f16 v[20:23], v[160:163], v[184:187], v[20:23]
	v_mfma_f32_16x16x32_f16 v[4:7], v[152:155], v[192:195], v[4:7]
	v_mfma_f32_16x16x32_f16 v[8:11], v[160:163], v[192:195], v[8:11]
	s_barrier
	s_add_i32 s68, 0, 0x18000
	s_add_i32 s69, 0, 0x1c000
	v_add_u32_e32 v144, s68, v227
	v_add_u32_e32 v160, s69, v227
	ds_read_b128 v[132:135], v144
	ds_read_b128 v[136:139], v144 offset:1024
	ds_read_b128 v[140:143], v144 offset:2048
	ds_read_b128 v[144:147], v144 offset:3072
	ds_read_b128 v[148:151], v160
	ds_read_b128 v[152:155], v160 offset:1024
	ds_read_b128 v[156:159], v160 offset:2048
	ds_read_b128 v[160:163], v160 offset:3072
	s_add_u32 s44, s44, 0x80000
	s_addc_u32 s45, s45, 0
	s_mov_b32 m0, s54
	v_lshl_add_u64 v[222:223], s[44:45], 0, v[0:1]
	ds_read_b128 v[164:167], v228 offset:32768
	ds_read_b128 v[168:171], v228 offset:33792
	ds_read_b128 v[172:175], v228 offset:34816
	ds_read_b128 v[176:179], v228 offset:35840
	ds_read_b128 v[180:183], v228 offset:36864
	ds_read_b128 v[184:187], v228 offset:37888
	ds_read_b128 v[188:191], v228 offset:38912
	ds_read_b128 v[192:195], v228 offset:39936
	global_load_lds_dwordx4 v[222:223], off
	v_lshl_add_u64 v[222:223], s[44:45], 0, v[208:209]
	s_mov_b32 m0, s55
	s_nop 0
	global_load_lds_dwordx4 v[222:223], off
	s_waitcnt vmcnt(8)
	s_waitcnt lgkmcnt(0)
	s_barrier
	v_mfma_f32_16x16x32_f16 v[128:131], v[132:135], v[164:167], v[128:131]
	v_mfma_f32_16x16x32_f16 v[124:127], v[140:143], v[164:167], v[124:127]
	v_mfma_f32_16x16x32_f16 v[112:115], v[132:135], v[172:175], v[112:115]
	v_mfma_f32_16x16x32_f16 v[108:111], v[140:143], v[172:175], v[108:111]
	v_mfma_f32_16x16x32_f16 v[96:99], v[132:135], v[180:183], v[96:99]
	v_mfma_f32_16x16x32_f16 v[92:95], v[140:143], v[180:183], v[92:95]
	v_mfma_f32_16x16x32_f16 v[80:83], v[132:135], v[188:191], v[80:83]
	v_mfma_f32_16x16x32_f16 v[76:79], v[140:143], v[188:191], v[76:79]
	v_mfma_f32_16x16x32_f16 v[128:131], v[136:139], v[168:171], v[128:131]
	v_mfma_f32_16x16x32_f16 v[124:127], v[144:147], v[168:171], v[124:127]
	v_mfma_f32_16x16x32_f16 v[112:115], v[136:139], v[176:179], v[112:115]
	v_mfma_f32_16x16x32_f16 v[108:111], v[144:147], v[176:179], v[108:111]
	v_mfma_f32_16x16x32_f16 v[96:99], v[136:139], v[184:187], v[96:99]
	v_mfma_f32_16x16x32_f16 v[92:95], v[144:147], v[184:187], v[92:95]
	v_mfma_f32_16x16x32_f16 v[80:83], v[136:139], v[192:195], v[80:83]
	v_mfma_f32_16x16x32_f16 v[76:79], v[144:147], v[192:195], v[76:79]
	v_mfma_f32_16x16x32_f16 v[120:123], v[148:151], v[164:167], v[120:123]
	v_mfma_f32_16x16x32_f16 v[116:119], v[156:159], v[164:167], v[116:119]
	v_mfma_f32_16x16x32_f16 v[104:107], v[148:151], v[172:175], v[104:107]
	v_mfma_f32_16x16x32_f16 v[100:103], v[156:159], v[172:175], v[100:103]
	v_mfma_f32_16x16x32_f16 v[88:91], v[148:151], v[180:183], v[88:91]
	v_mfma_f32_16x16x32_f16 v[84:87], v[156:159], v[180:183], v[84:87]
	v_mfma_f32_16x16x32_f16 v[68:71], v[148:151], v[188:191], v[68:71]
	v_mfma_f32_16x16x32_f16 v[72:75], v[156:159], v[188:191], v[72:75]
	v_mfma_f32_16x16x32_f16 v[120:123], v[152:155], v[168:171], v[120:123]
	v_mfma_f32_16x16x32_f16 v[116:119], v[160:163], v[168:171], v[116:119]
	v_mfma_f32_16x16x32_f16 v[104:107], v[152:155], v[176:179], v[104:107]
	v_mfma_f32_16x16x32_f16 v[100:103], v[160:163], v[176:179], v[100:103]
	v_mfma_f32_16x16x32_f16 v[88:91], v[152:155], v[184:187], v[88:91]
	v_mfma_f32_16x16x32_f16 v[84:87], v[160:163], v[184:187], v[84:87]
	v_mfma_f32_16x16x32_f16 v[68:71], v[152:155], v[192:195], v[68:71]
	v_mfma_f32_16x16x32_f16 v[72:75], v[160:163], v[192:195], v[72:75]
	s_barrier
; #define PG8_STAGE(bufoff, gbase, voff) do { _Pragma("unroll") for (int _i = 0; _i < 2; ++_i) \
;         __builtin_amdgcn_global_load_lds((const unsigned*)((const char*)(gbase) + (voff)[_i]), (LAS unsigned*)(lds + (bufoff) + ldsw + _i * 8192), 16, 0, 0); } while (0)
; #define PG8_LDA(dst, b, h) do { _Pragma("unroll") for (int m = 0; m < 4; ++m) _Pragma("unroll") for (int k = 0; k < 2; ++k) dst[m][k] = *(const LAS bf16x8*)(lds + PG8_SA(b, h) + aoff + m * 2048 + k * 1024); } while (0)
; #define PG8_WAIT_V(n) asm volatile("s_waitcnt vmcnt(" #n ")" ::: "memory")
; #define PG8_WAIT_L(n) asm volatile("s_waitcnt lgkmcnt(" #n ")" ::: "memory")
; #define PG8_BAR __builtin_amdgcn_s_barrier()
; #define PG8_SCHED __builtin_amdgcn_sched_barrier(0)
; template <class Epi, class Sched, bool FUSED = false, bool APERM = false>
; __device__ __forceinline__ void gemm_phase(int wid_s, LAS unsigned char* lds, const Gemm g, const Sched& S, const Epi& E) {
;     ...
;             PG8_LDA(At, 1, 1); PG8_STAGE(PG8_SB(1, 0), b3, voffB); PG8_STAGE(PG8_SB(1, 1), b3 + hstep, voffB); PG8_STAGE(PG8_SA(1, 0), a3, voffA);
;             PG8_WAIT_V(8); PG8_WAIT_L(0); PG8_BAR; PG8_MMA(1, 0, At, B0); PG8_MMA(1, 1, At, B1); PG8_BAR; PG8_SCHED;
;         }
;         if (wr == 0) PG8_BAR;
	s_add_i32 s44, s68, s51
	v_lshl_add_u64 v[214:215], v[214:215], 0, s[12:13]
	s_mov_b32 m0, s44
	ds_read_b128 v[164:167], v228 offset:49152
	ds_read_b128 v[168:171], v228 offset:50176
	ds_read_b128 v[172:175], v228 offset:51200
	ds_read_b128 v[176:179], v228 offset:52224
	ds_read_b128 v[180:183], v228 offset:53248
	ds_read_b128 v[184:187], v228 offset:54272
	ds_read_b128 v[188:191], v228 offset:55296
	ds_read_b128 v[192:195], v228 offset:56320
	global_load_lds_dwordx4 v[214:215], off
	s_add_i32 m0, s44, 0x2000
	s_add_u32 s42, s42, 0x80080
	v_lshl_add_u64 v[214:215], v[216:217], 0, s[12:13]
	s_addc_u32 s43, s43, 0
	s_add_i32 s44, s69, s51
	global_load_lds_dwordx4 v[214:215], off
	v_lshl_add_u64 v[214:215], s[42:43], 0, v[0:1]
	s_mov_b32 m0, s44
	s_nop 0
	global_load_lds_dwordx4 v[214:215], off
	v_lshl_add_u64 v[214:215], s[42:43], 0, v[208:209]
	s_add_i32 m0, s44, 0x2000
	s_nop 0
	global_load_lds_dwordx4 v[214:215], off
	v_lshl_add_u64 v[214:215], v[218:219], 0, s[12:13]
	s_mov_b32 m0, s59
	s_nop 0
	global_load_lds_dwordx4 v[214:215], off
	v_lshl_add_u64 v[214:215], v[220:221], 0, s[12:13]
	s_mov_b32 m0, s60
	s_nop 0
	global_load_lds_dwordx4 v[214:215], off
	s_waitcnt vmcnt(8)
	s_waitcnt lgkmcnt(0)
	s_barrier
	v_mfma_f32_16x16x32_f16 v[64:67], v[132:135], v[164:167], v[64:67]
	v_mfma_f32_16x16x32_f16 v[60:63], v[140:143], v[164:167], v[60:63]
	v_mfma_f32_16x16x32_f16 v[48:51], v[132:135], v[172:175], v[48:51]
	v_mfma_f32_16x16x32_f16 v[44:47], v[140:143], v[172:175], v[44:47]
	v_mfma_f32_16x16x32_f16 v[32:35], v[132:135], v[180:183], v[32:35]
	v_mfma_f32_16x16x32_f16 v[28:31], v[140:143], v[180:183], v[28:31]
	v_mfma_f32_16x16x32_f16 v[12:15], v[132:135], v[188:191], v[12:15]
	v_mfma_f32_16x16x32_f16 v[16:19], v[140:143], v[188:191], v[16:19]
	v_mfma_f32_16x16x32_f16 v[64:67], v[136:139], v[168:171], v[64:67]
	v_mfma_f32_16x16x32_f16 v[60:63], v[144:147], v[168:171], v[60:63]
	v_mfma_f32_16x16x32_f16 v[48:51], v[136:139], v[176:179], v[48:51]
	v_mfma_f32_16x16x32_f16 v[44:47], v[144:147], v[176:179], v[44:47]
	v_mfma_f32_16x16x32_f16 v[32:35], v[136:139], v[184:187], v[32:35]
	v_mfma_f32_16x16x32_f16 v[28:31], v[144:147], v[184:187], v[28:31]
	v_mfma_f32_16x16x32_f16 v[12:15], v[136:139], v[192:195], v[12:15]
	v_mfma_f32_16x16x32_f16 v[16:19], v[144:147], v[192:195], v[16:19]
	v_mfma_f32_16x16x32_f16 v[56:59], v[148:151], v[164:167], v[56:59]
	v_mfma_f32_16x16x32_f16 v[52:55], v[156:159], v[164:167], v[52:55]
	v_mfma_f32_16x16x32_f16 v[40:43], v[148:151], v[172:175], v[40:43]
	v_mfma_f32_16x16x32_f16 v[36:39], v[156:159], v[172:175], v[36:39]
	v_mfma_f32_16x16x32_f16 v[24:27], v[148:151], v[180:183], v[24:27]
	v_mfma_f32_16x16x32_f16 v[20:23], v[156:159], v[180:183], v[20:23]
	v_mfma_f32_16x16x32_f16 v[4:7], v[148:151], v[188:191], v[4:7]
	v_mfma_f32_16x16x32_f16 v[8:11], v[156:159], v[188:191], v[8:11]
	v_mfma_f32_16x16x32_f16 v[56:59], v[152:155], v[168:171], v[56:59]
	v_mfma_f32_16x16x32_f16 v[52:55], v[160:163], v[168:171], v[52:55]
	v_mfma_f32_16x16x32_f16 v[40:43], v[152:155], v[176:179], v[40:43]
	v_mfma_f32_16x16x32_f16 v[36:39], v[160:163], v[176:179], v[36:39]
	v_mfma_f32_16x16x32_f16 v[24:27], v[152:155], v[184:187], v[24:27]
	v_mfma_f32_16x16x32_f16 v[20:23], v[160:163], v[184:187], v[20:23]
	v_mfma_f32_16x16x32_f16 v[4:7], v[152:155], v[192:195], v[4:7]
	v_mfma_f32_16x16x32_f16 v[8:11], v[160:163], v[192:195], v[8:11]
	s_barrier
	s_add_i32 s67, s67, 2
	s_add_u32 s35, s35, 0x100
	s_addc_u32 s66, s66, 0
	s_add_u32 s40, s40, 0x100
	s_addc_u32 s41, s41, 0
	s_cmp_gt_u32 s67, 29
	s_cbranch_scc0 .LBB0_145
	s_and_b64 vcc, exec, s[16:17]
	s_cbranch_vccz .LBB0_148
	s_barrier

; #define PG8_STAGE(bufoff, gbase, voff) do { _Pragma("unroll") for (int _i = 0; _i < 2; ++_i) \
;         __builtin_amdgcn_global_load_lds((const unsigned*)((const char*)(gbase) + (voff)[_i]), (LAS unsigned*)(lds + (bufoff) + ldsw + _i * 8192), 16, 0, 0); } while (0)
; #define PG8_LDA(dst, b, h) do { _Pragma("unroll") for (int m = 0; m < 4; ++m) _Pragma("unroll") for (int k = 0; k < 2; ++k) dst[m][k] = *(const LAS bf16x8*)(lds + PG8_SA(b, h) + aoff + m * 2048 + k * 1024); } while (0)
; #define PG8_LDB(dst, b, h) do { _Pragma("unroll") for (int n = 0; n < 2; ++n) _Pragma("unroll") for (int k = 0; k < 2; ++k) dst[n][k] = *(const LAS bf16x8*)(lds + PG8_SB(b, h) + boff + n * 2048 + k * 1024); } while (0)
; #define PG8_WAIT_V(n) asm volatile("s_waitcnt vmcnt(" #n ")" ::: "memory")
; #define PG8_WAIT_L(n) asm volatile("s_waitcnt lgkmcnt(" #n ")" ::: "memory")
; #define PG8_BAR __builtin_amdgcn_s_barrier()
; #define PG8_SCHED __builtin_amdgcn_sched_barrier(0)
; template <class Epi, class Sched, bool FUSED = false, bool APERM = false>
; __device__ __forceinline__ void gemm_phase(int wid_s, LAS unsigned char* lds, const Gemm g, const Sched& S, const Epi& E) {
;     ...
;             const bool last = (t == nt - 2);
;             const char* a1 = cA + (size_t)(t + 1) * kstep;
;             const char* a2 = last ? nA : cA + (size_t)(t + 2) * kstep; const char* b2 = last ? nB : cB + (size_t)(t + 2) * kstep;
;             const char* a3 = a2 + kstep; const char* b3 = b2 + kstep;
;             if (last && has_next) S.a_ready(nxt);
;             PG8_LDB(B0, 0, 0); PG8_LDB(B1, 0, 1); PG8_SCHED; PG8_LDA(At, 0, 0); PG8_STAGE(PG8_SA(1, 1), a1 + hstep, voffA);
;             PG8_WAIT_V(8); PG8_WAIT_L(0); PG8_BAR; PG8_MMA(0, 0, At, B0); PG8_MMA(0, 1, At, B1); PG8_BAR; PG8_SCHED;
;             PG8_LDA(At, 0, 1); PG8_STAGE(PG8_SB(0, 0), b2, voffB); PG8_STAGE(PG8_SB(0, 1), b2 + hstep, voffB); PG8_STAGE(PG8_SA(0, 0), a2, voffA);
.LBB0_342:
	s_add_u32 s38, s36, 0xfff80080
	s_addc_u32 s39, s37, -1
	s_add_i32 s64, 0, 0x10000
	s_cmp_eq_u32 s63, 28
	s_cselect_b32 s41, s1, s39
	s_cselect_b32 s40, s23, s38
	s_cselect_b32 s39, s25, s62
	s_cselect_b32 s38, s35, s61
	s_add_i32 s66, 0, 0x14000
	v_add_u32_e32 v144, s64, v227
	v_add_u32_e32 v160, s66, v227
	ds_read_b128 v[132:135], v144
	ds_read_b128 v[136:139], v144 offset:1024
	ds_read_b128 v[140:143], v144 offset:2048
	ds_read_b128 v[144:147], v144 offset:3072
	ds_read_b128 v[148:151], v160
	ds_read_b128 v[152:155], v160 offset:1024
	ds_read_b128 v[156:159], v160 offset:2048
	ds_read_b128 v[160:163], v160 offset:3072
	v_lshl_add_u64 v[214:215], s[36:37], 0, v[212:213]
	s_add_i32 m0, s48, 0xc000
	ds_read_b128 v[164:167], v228
	ds_read_b128 v[168:171], v228 offset:1024
	ds_read_b128 v[172:175], v228 offset:2048
	ds_read_b128 v[176:179], v228 offset:3072
	ds_read_b128 v[180:183], v228 offset:4096
	ds_read_b128 v[184:187], v228 offset:5120
	ds_read_b128 v[188:191], v228 offset:6144
	ds_read_b128 v[192:195], v228 offset:7168
	global_load_lds_dwordx4 v[214:215], off
	v_lshl_add_u64 v[214:215], s[36:37], 0, v[210:211]
	s_add_i32 m0, s48, 0xe000
	s_nop 0
	global_load_lds_dwordx4 v[214:215], off
	s_waitcnt vmcnt(8)
	s_waitcnt lgkmcnt(0)
	s_barrier
	v_mfma_f32_16x16x32_f16 v[128:131], v[132:135], v[164:167], v[128:131]
	v_mfma_f32_16x16x32_f16 v[124:127], v[140:143], v[164:167], v[124:127]
	v_mfma_f32_16x16x32_f16 v[112:115], v[132:135], v[172:175], v[112:115]
	v_mfma_f32_16x16x32_f16 v[108:111], v[140:143], v[172:175], v[108:111]
	v_mfma_f32_16x16x32_f16 v[96:99], v[132:135], v[180:183], v[96:99]
	v_mfma_f32_16x16x32_f16 v[92:95], v[140:143], v[180:183], v[92:95]
	v_mfma_f32_16x16x32_f16 v[80:83], v[132:135], v[188:191], v[80:83]
	v_mfma_f32_16x16x32_f16 v[76:79], v[140:143], v[188:191], v[76:79]
	v_mfma_f32_16x16x32_f16 v[128:131], v[136:139], v[168:171], v[128:131]
	v_mfma_f32_16x16x32_f16 v[124:127], v[144:147], v[168:171], v[124:127]
	v_mfma_f32_16x16x32_f16 v[112:115], v[136:139], v[176:179], v[112:115]
	v_mfma_f32_16x16x32_f16 v[108:111], v[144:147], v[176:179], v[108:111]
	v_mfma_f32_16x16x32_f16 v[96:99], v[136:139], v[184:187], v[96:99]
	v_mfma_f32_16x16x32_f16 v[92:95], v[144:147], v[184:187], v[92:95]
	v_mfma_f32_16x16x32_f16 v[80:83], v[136:139], v[192:195], v[80:83]
	v_mfma_f32_16x16x32_f16 v[76:79], v[144:147], v[192:195], v[76:79]
	v_mfma_f32_16x16x32_f16 v[120:123], v[148:151], v[164:167], v[120:123]
	v_mfma_f32_16x16x32_f16 v[116:119], v[156:159], v[164:167], v[116:119]
	v_mfma_f32_16x16x32_f16 v[104:107], v[148:151], v[172:175], v[104:107]
	v_mfma_f32_16x16x32_f16 v[100:103], v[156:159], v[172:175], v[100:103]
	v_mfma_f32_16x16x32_f16 v[88:91], v[148:151], v[180:183], v[88:91]
	v_mfma_f32_16x16x32_f16 v[84:87], v[156:159], v[180:183], v[84:87]
	v_mfma_f32_16x16x32_f16 v[68:71], v[148:151], v[188:191], v[68:71]
	v_mfma_f32_16x16x32_f16 v[72:75], v[156:159], v[188:191], v[72:75]
	v_mfma_f32_16x16x32_f16 v[120:123], v[152:155], v[168:171], v[120:123]
	v_mfma_f32_16x16x32_f16 v[116:119], v[160:163], v[168:171], v[116:119]
	v_mfma_f32_16x16x32_f16 v[104:107], v[152:155], v[176:179], v[104:107]
	v_mfma_f32_16x16x32_f16 v[100:103], v[160:163], v[176:179], v[100:103]
	v_mfma_f32_16x16x32_f16 v[88:91], v[152:155], v[184:187], v[88:91]
	v_mfma_f32_16x16x32_f16 v[84:87], v[160:163], v[184:187], v[84:87]
	v_mfma_f32_16x16x32_f16 v[68:71], v[152:155], v[192:195], v[68:71]
	v_mfma_f32_16x16x32_f16 v[72:75], v[160:163], v[192:195], v[72:75]
	s_barrier
	s_add_i32 s64, s64, s47
	v_lshl_add_u64 v[214:215], s[38:39], 0, v[0:1]
	s_mov_b32 m0, s64
	ds_read_b128 v[164:167], v228 offset:16384
	ds_read_b128 v[168:171], v228 offset:17408
	ds_read_b128 v[172:175], v228 offset:18432
	ds_read_b128 v[176:179], v228 offset:19456
	ds_read_b128 v[180:183], v228 offset:20480
	ds_read_b128 v[184:187], v228 offset:21504
	ds_read_b128 v[188:191], v228 offset:22528
	ds_read_b128 v[192:195], v228 offset:23552
	global_load_lds_dwordx4 v[214:215], off
	s_add_i32 m0, s64, 0x2000
	s_add_u32 s64, s38, 0x80000
	v_lshl_add_u64 v[216:217], s[38:39], 0, v[208:209]
	s_addc_u32 s65, s39, 0
	s_add_i32 s66, s66, s47
	global_load_lds_dwordx4 v[216:217], off
	v_lshl_add_u64 v[218:219], s[64:65], 0, v[0:1]
	s_mov_b32 m0, s66
	v_lshl_add_u64 v[220:221], s[40:41], 0, v[208:209]
	global_load_lds_dwordx4 v[218:219], off
	v_lshl_add_u64 v[218:219], s[64:65], 0, v[208:209]
	s_add_i32 m0, s66, 0x2000
	s_nop 0
	global_load_lds_dwordx4 v[218:219], off
	v_lshl_add_u64 v[218:219], s[40:41], 0, v[0:1]
	s_mov_b32 m0, s48
	s_nop 0
	global_load_lds_dwordx4 v[218:219], off
	s_mov_b32 m0, s49
	s_nop 0
	global_load_lds_dwordx4 v[220:221], off
	s_waitcnt vmcnt(8)
	s_waitcnt lgkmcnt(0)
	s_barrier
; #define PG8_STAGE(bufoff, gbase, voff) do { _Pragma("unroll") for (int _i = 0; _i < 2; ++_i) \
;         __builtin_amdgcn_global_load_lds((const unsigned*)((const char*)(gbase) + (voff)[_i]), (LAS unsigned*)(lds + (bufoff) + ldsw + _i * 8192), 16, 0, 0); } while (0)
; #define PG8_LDA(dst, b, h) do { _Pragma("unroll") for (int m = 0; m < 4; ++m) _Pragma("unroll") for (int k = 0; k < 2; ++k) dst[m][k] = *(const LAS bf16x8*)(lds + PG8_SA(b, h) + aoff + m * 2048 + k * 1024); } while (0)
; #define PG8_LDB(dst, b, h) do { _Pragma("unroll") for (int n = 0; n < 2; ++n) _Pragma("unroll") for (int k = 0; k < 2; ++k) dst[n][k] = *(const LAS bf16x8*)(lds + PG8_SB(b, h) + boff + n * 2048 + k * 1024); } while (0)
; #define PG8_WAIT_V(n) asm volatile("s_waitcnt vmcnt(" #n ")" ::: "memory")
; #define PG8_WAIT_L(n) asm volatile("s_waitcnt lgkmcnt(" #n ")" ::: "memory")
; #define PG8_BAR __builtin_amdgcn_s_barrier()
; #define PG8_SCHED __builtin_amdgcn_sched_barrier(0)
; template <class Epi, class Sched, bool FUSED = false, bool APERM = false>
; __device__ __forceinline__ void gemm_phase(int wid_s, LAS unsigned char* lds, const Gemm g, const Sched& S, const Epi& E) {
;     ...
;             PG8_WAIT_V(8); PG8_WAIT_L(0); PG8_BAR; PG8_MMA(1, 0, At, B0); PG8_MMA(1, 1, At, B1); PG8_BAR; PG8_SCHED;
;             PG8_LDB(B0, 1, 0); PG8_LDB(B1, 1, 1); PG8_SCHED; PG8_LDA(At, 1, 0); PG8_STAGE(PG8_SA(0, 1), a2 + hstep, voffA);
;             PG8_WAIT_V(8); PG8_WAIT_L(0); PG8_BAR; PG8_MMA(0, 0, At, B0); PG8_MMA(0, 1, At, B1); PG8_BAR; PG8_SCHED;
	v_mfma_f32_16x16x32_f16 v[64:67], v[132:135], v[164:167], v[64:67]
	v_mfma_f32_16x16x32_f16 v[60:63], v[140:143], v[164:167], v[60:63]
	v_mfma_f32_16x16x32_f16 v[48:51], v[132:135], v[172:175], v[48:51]
	v_mfma_f32_16x16x32_f16 v[44:47], v[140:143], v[172:175], v[44:47]
	v_mfma_f32_16x16x32_f16 v[32:35], v[132:135], v[180:183], v[32:35]
	v_mfma_f32_16x16x32_f16 v[28:31], v[140:143], v[180:183], v[28:31]
	v_mfma_f32_16x16x32_f16 v[12:15], v[132:135], v[188:191], v[12:15]
	v_mfma_f32_16x16x32_f16 v[16:19], v[140:143], v[188:191], v[16:19]
	v_mfma_f32_16x16x32_f16 v[64:67], v[136:139], v[168:171], v[64:67]
	v_mfma_f32_16x16x32_f16 v[60:63], v[144:147], v[168:171], v[60:63]
	v_mfma_f32_16x16x32_f16 v[48:51], v[136:139], v[176:179], v[48:51]
	v_mfma_f32_16x16x32_f16 v[44:47], v[144:147], v[176:179], v[44:47]
	v_mfma_f32_16x16x32_f16 v[32:35], v[136:139], v[184:187], v[32:35]
	v_mfma_f32_16x16x32_f16 v[28:31], v[144:147], v[184:187], v[28:31]
	v_mfma_f32_16x16x32_f16 v[12:15], v[136:139], v[192:195], v[12:15]
	v_mfma_f32_16x16x32_f16 v[16:19], v[144:147], v[192:195], v[16:19]
	v_mfma_f32_16x16x32_f16 v[56:59], v[148:151], v[164:167], v[56:59]
	v_mfma_f32_16x16x32_f16 v[52:55], v[156:159], v[164:167], v[52:55]
	v_mfma_f32_16x16x32_f16 v[40:43], v[148:151], v[172:175], v[40:43]
	v_mfma_f32_16x16x32_f16 v[36:39], v[156:159], v[172:175], v[36:39]
	v_mfma_f32_16x16x32_f16 v[24:27], v[148:151], v[180:183], v[24:27]
	v_mfma_f32_16x16x32_f16 v[20:23], v[156:159], v[180:183], v[20:23]
	v_mfma_f32_16x16x32_f16 v[4:7], v[148:151], v[188:191], v[4:7]
	v_mfma_f32_16x16x32_f16 v[8:11], v[156:159], v[188:191], v[8:11]
	v_mfma_f32_16x16x32_f16 v[56:59], v[152:155], v[168:171], v[56:59]
	v_mfma_f32_16x16x32_f16 v[52:55], v[160:163], v[168:171], v[52:55]
	v_mfma_f32_16x16x32_f16 v[40:43], v[152:155], v[176:179], v[40:43]
	v_mfma_f32_16x16x32_f16 v[36:39], v[160:163], v[176:179], v[36:39]
	v_mfma_f32_16x16x32_f16 v[24:27], v[152:155], v[184:187], v[24:27]
	v_mfma_f32_16x16x32_f16 v[20:23], v[160:163], v[184:187], v[20:23]
	v_mfma_f32_16x16x32_f16 v[4:7], v[152:155], v[192:195], v[4:7]
	v_mfma_f32_16x16x32_f16 v[8:11], v[160:163], v[192:195], v[8:11]
	s_barrier
	s_add_i32 s64, 0, 0x18000
	s_add_i32 s65, 0, 0x1c000
	v_add_u32_e32 v144, s64, v227
	v_add_u32_e32 v160, s65, v227
	ds_read_b128 v[132:135], v144
	ds_read_b128 v[136:139], v144 offset:1024
	ds_read_b128 v[140:143], v144 offset:2048
	ds_read_b128 v[144:147], v144 offset:3072
	ds_read_b128 v[148:151], v160
	ds_read_b128 v[152:155], v160 offset:1024
	ds_read_b128 v[156:159], v160 offset:2048
	ds_read_b128 v[160:163], v160 offset:3072
	s_add_u32 s40, s40, 0x80000
	s_addc_u32 s41, s41, 0
	s_mov_b32 m0, s50
	v_lshl_add_u64 v[222:223], s[40:41], 0, v[0:1]
	ds_read_b128 v[164:167], v228 offset:32768
	ds_read_b128 v[168:171], v228 offset:33792
	ds_read_b128 v[172:175], v228 offset:34816
	ds_read_b128 v[176:179], v228 offset:35840
	ds_read_b128 v[180:183], v228 offset:36864
	ds_read_b128 v[184:187], v228 offset:37888
	ds_read_b128 v[188:191], v228 offset:38912
	ds_read_b128 v[192:195], v228 offset:39936
	global_load_lds_dwordx4 v[222:223], off
	v_lshl_add_u64 v[222:223], s[40:41], 0, v[208:209]
	s_mov_b32 m0, s51
	s_nop 0
	global_load_lds_dwordx4 v[222:223], off
	s_waitcnt vmcnt(8)
	s_waitcnt lgkmcnt(0)
	s_barrier
	v_mfma_f32_16x16x32_f16 v[128:131], v[132:135], v[164:167], v[128:131]
	v_mfma_f32_16x16x32_f16 v[124:127], v[140:143], v[164:167], v[124:127]
	v_mfma_f32_16x16x32_f16 v[112:115], v[132:135], v[172:175], v[112:115]
	v_mfma_f32_16x16x32_f16 v[108:111], v[140:143], v[172:175], v[108:111]
	v_mfma_f32_16x16x32_f16 v[96:99], v[132:135], v[180:183], v[96:99]
	v_mfma_f32_16x16x32_f16 v[92:95], v[140:143], v[180:183], v[92:95]
	v_mfma_f32_16x16x32_f16 v[80:83], v[132:135], v[188:191], v[80:83]
	v_mfma_f32_16x16x32_f16 v[76:79], v[140:143], v[188:191], v[76:79]
	v_mfma_f32_16x16x32_f16 v[128:131], v[136:139], v[168:171], v[128:131]
	v_mfma_f32_16x16x32_f16 v[124:127], v[144:147], v[168:171], v[124:127]
	v_mfma_f32_16x16x32_f16 v[112:115], v[136:139], v[176:179], v[112:115]
	v_mfma_f32_16x16x32_f16 v[108:111], v[144:147], v[176:179], v[108:111]
	v_mfma_f32_16x16x32_f16 v[96:99], v[136:139], v[184:187], v[96:99]
	v_mfma_f32_16x16x32_f16 v[92:95], v[144:147], v[184:187], v[92:95]
	v_mfma_f32_16x16x32_f16 v[80:83], v[136:139], v[192:195], v[80:83]
	v_mfma_f32_16x16x32_f16 v[76:79], v[144:147], v[192:195], v[76:79]
	v_mfma_f32_16x16x32_f16 v[120:123], v[148:151], v[164:167], v[120:123]
	v_mfma_f32_16x16x32_f16 v[116:119], v[156:159], v[164:167], v[116:119]
	v_mfma_f32_16x16x32_f16 v[104:107], v[148:151], v[172:175], v[104:107]
	v_mfma_f32_16x16x32_f16 v[100:103], v[156:159], v[172:175], v[100:103]
	v_mfma_f32_16x16x32_f16 v[88:91], v[148:151], v[180:183], v[88:91]
	v_mfma_f32_16x16x32_f16 v[84:87], v[156:159], v[180:183], v[84:87]
	v_mfma_f32_16x16x32_f16 v[68:71], v[148:151], v[188:191], v[68:71]
	v_mfma_f32_16x16x32_f16 v[72:75], v[156:159], v[188:191], v[72:75]
	v_mfma_f32_16x16x32_f16 v[120:123], v[152:155], v[168:171], v[120:123]
	v_mfma_f32_16x16x32_f16 v[116:119], v[160:163], v[168:171], v[116:119]
	v_mfma_f32_16x16x32_f16 v[104:107], v[152:155], v[176:179], v[104:107]
	v_mfma_f32_16x16x32_f16 v[100:103], v[160:163], v[176:179], v[100:103]
	v_mfma_f32_16x16x32_f16 v[88:91], v[152:155], v[184:187], v[88:91]
	v_mfma_f32_16x16x32_f16 v[84:87], v[160:163], v[184:187], v[84:87]
	v_mfma_f32_16x16x32_f16 v[68:71], v[152:155], v[192:195], v[68:71]
	v_mfma_f32_16x16x32_f16 v[72:75], v[160:163], v[192:195], v[72:75]
	s_barrier
; #define PG8_STAGE(bufoff, gbase, voff) do { _Pragma("unroll") for (int _i = 0; _i < 2; ++_i) \
;         __builtin_amdgcn_global_load_lds((const unsigned*)((const char*)(gbase) + (voff)[_i]), (LAS unsigned*)(lds + (bufoff) + ldsw + _i * 8192), 16, 0, 0); } while (0)
; #define PG8_LDA(dst, b, h) do { _Pragma("unroll") for (int m = 0; m < 4; ++m) _Pragma("unroll") for (int k = 0; k < 2; ++k) dst[m][k] = *(const LAS bf16x8*)(lds + PG8_SA(b, h) + aoff + m * 2048 + k * 1024); } while (0)
; #define PG8_WAIT_V(n) asm volatile("s_waitcnt vmcnt(" #n ")" ::: "memory")
; #define PG8_WAIT_L(n) asm volatile("s_waitcnt lgkmcnt(" #n ")" ::: "memory")
; #define PG8_BAR __builtin_amdgcn_s_barrier()
; #define PG8_SCHED __builtin_amdgcn_sched_barrier(0)
; template <class Epi, class Sched, bool FUSED = false, bool APERM = false>
; __device__ __forceinline__ void gemm_phase(int wid_s, LAS unsigned char* lds, const Gemm g, const Sched& S, const Epi& E) {
;     ...
;             PG8_LDA(At, 1, 1); PG8_STAGE(PG8_SB(1, 0), b3, voffB); PG8_STAGE(PG8_SB(1, 1), b3 + hstep, voffB); PG8_STAGE(PG8_SA(1, 0), a3, voffA);
;             PG8_WAIT_V(8); PG8_WAIT_L(0); PG8_BAR; PG8_MMA(1, 0, At, B0); PG8_MMA(1, 1, At, B1); PG8_BAR; PG8_SCHED;
;         }
;         if (wr == 0) PG8_BAR;
	s_add_i32 s40, s64, s47
	v_lshl_add_u64 v[214:215], v[214:215], 0, s[12:13]
	s_mov_b32 m0, s40
	ds_read_b128 v[164:167], v228 offset:49152
	ds_read_b128 v[168:171], v228 offset:50176
	ds_read_b128 v[172:175], v228 offset:51200
	ds_read_b128 v[176:179], v228 offset:52224
	ds_read_b128 v[180:183], v228 offset:53248
	ds_read_b128 v[184:187], v228 offset:54272
	ds_read_b128 v[188:191], v228 offset:55296
	ds_read_b128 v[192:195], v228 offset:56320
	global_load_lds_dwordx4 v[214:215], off
	s_add_i32 m0, s40, 0x2000
	s_add_u32 s38, s38, 0x80080
	v_lshl_add_u64 v[214:215], v[216:217], 0, s[12:13]
	s_addc_u32 s39, s39, 0
	s_add_i32 s40, s65, s47
	global_load_lds_dwordx4 v[214:215], off
	v_lshl_add_u64 v[214:215], s[38:39], 0, v[0:1]
	s_mov_b32 m0, s40
	s_nop 0
	global_load_lds_dwordx4 v[214:215], off
	v_lshl_add_u64 v[214:215], s[38:39], 0, v[208:209]
	s_add_i32 m0, s40, 0x2000
	s_nop 0
	global_load_lds_dwordx4 v[214:215], off
	v_lshl_add_u64 v[214:215], v[218:219], 0, s[12:13]
	s_mov_b32 m0, s55
	s_nop 0
	global_load_lds_dwordx4 v[214:215], off
	v_lshl_add_u64 v[214:215], v[220:221], 0, s[12:13]
	s_mov_b32 m0, s56
	s_nop 0
	global_load_lds_dwordx4 v[214:215], off
	s_waitcnt vmcnt(8)
	s_waitcnt lgkmcnt(0)
	s_barrier
	v_mfma_f32_16x16x32_f16 v[64:67], v[132:135], v[164:167], v[64:67]
	v_mfma_f32_16x16x32_f16 v[60:63], v[140:143], v[164:167], v[60:63]
	v_mfma_f32_16x16x32_f16 v[48:51], v[132:135], v[172:175], v[48:51]
	v_mfma_f32_16x16x32_f16 v[44:47], v[140:143], v[172:175], v[44:47]
	v_mfma_f32_16x16x32_f16 v[32:35], v[132:135], v[180:183], v[32:35]
	v_mfma_f32_16x16x32_f16 v[28:31], v[140:143], v[180:183], v[28:31]
	v_mfma_f32_16x16x32_f16 v[12:15], v[132:135], v[188:191], v[12:15]
	v_mfma_f32_16x16x32_f16 v[16:19], v[140:143], v[188:191], v[16:19]
	v_mfma_f32_16x16x32_f16 v[64:67], v[136:139], v[168:171], v[64:67]
	v_mfma_f32_16x16x32_f16 v[60:63], v[144:147], v[168:171], v[60:63]
	v_mfma_f32_16x16x32_f16 v[48:51], v[136:139], v[176:179], v[48:51]
	v_mfma_f32_16x16x32_f16 v[44:47], v[144:147], v[176:179], v[44:47]
	v_mfma_f32_16x16x32_f16 v[32:35], v[136:139], v[184:187], v[32:35]
	v_mfma_f32_16x16x32_f16 v[28:31], v[144:147], v[184:187], v[28:31]
	v_mfma_f32_16x16x32_f16 v[12:15], v[136:139], v[192:195], v[12:15]
	v_mfma_f32_16x16x32_f16 v[16:19], v[144:147], v[192:195], v[16:19]
	v_mfma_f32_16x16x32_f16 v[56:59], v[148:151], v[164:167], v[56:59]
	v_mfma_f32_16x16x32_f16 v[52:55], v[156:159], v[164:167], v[52:55]
	v_mfma_f32_16x16x32_f16 v[40:43], v[148:151], v[172:175], v[40:43]
	v_mfma_f32_16x16x32_f16 v[36:39], v[156:159], v[172:175], v[36:39]
	v_mfma_f32_16x16x32_f16 v[24:27], v[148:151], v[180:183], v[24:27]
	v_mfma_f32_16x16x32_f16 v[20:23], v[156:159], v[180:183], v[20:23]
	v_mfma_f32_16x16x32_f16 v[4:7], v[148:151], v[188:191], v[4:7]
	v_mfma_f32_16x16x32_f16 v[8:11], v[156:159], v[188:191], v[8:11]
	v_mfma_f32_16x16x32_f16 v[56:59], v[152:155], v[168:171], v[56:59]
	v_mfma_f32_16x16x32_f16 v[52:55], v[160:163], v[168:171], v[52:55]
	v_mfma_f32_16x16x32_f16 v[40:43], v[152:155], v[176:179], v[40:43]
	v_mfma_f32_16x16x32_f16 v[36:39], v[160:163], v[176:179], v[36:39]
	v_mfma_f32_16x16x32_f16 v[24:27], v[152:155], v[184:187], v[24:27]
	v_mfma_f32_16x16x32_f16 v[20:23], v[160:163], v[184:187], v[20:23]
	v_mfma_f32_16x16x32_f16 v[4:7], v[152:155], v[192:195], v[4:7]
	v_mfma_f32_16x16x32_f16 v[8:11], v[160:163], v[192:195], v[8:11]
	s_barrier
	s_add_i32 s63, s63, 2
	s_add_u32 s61, s61, 0x100
	s_addc_u32 s62, s62, 0
	s_add_u32 s36, s36, 0x100
	s_addc_u32 s37, s37, 0
	s_cmp_gt_u32 s63, 29
	s_cbranch_scc0 .LBB0_342
	s_and_b64 vcc, exec, s[14:15]
	s_cbranch_vccz .LBB0_345
	s_barrier

; #define PG8_STAGE(bufoff, gbase, voff) do { _Pragma("unroll") for (int _i = 0; _i < 2; ++_i) \
;         __builtin_amdgcn_global_load_lds((const unsigned*)((const char*)(gbase) + (voff)[_i]), (LAS unsigned*)(lds + (bufoff) + ldsw + _i * 8192), 16, 0, 0); } while (0)
; #define PG8_LDA(dst, b, h) do { _Pragma("unroll") for (int m = 0; m < 4; ++m) _Pragma("unroll") for (int k = 0; k < 2; ++k) dst[m][k] = *(const LAS bf16x8*)(lds + PG8_SA(b, h) + aoff + m * 2048 + k * 1024); } while (0)
; #define PG8_LDB(dst, b, h) do { _Pragma("unroll") for (int n = 0; n < 2; ++n) _Pragma("unroll") for (int k = 0; k < 2; ++k) dst[n][k] = *(const LAS bf16x8*)(lds + PG8_SB(b, h) + boff + n * 2048 + k * 1024); } while (0)
; #define PG8_WAIT_V(n) asm volatile("s_waitcnt vmcnt(" #n ")" ::: "memory")
; #define PG8_WAIT_L(n) asm volatile("s_waitcnt lgkmcnt(" #n ")" ::: "memory")
; #define PG8_BAR __builtin_amdgcn_s_barrier()
; #define PG8_SCHED __builtin_amdgcn_sched_barrier(0)
; template <class Epi, class Sched, bool FUSED = false, bool APERM = false>
; __device__ __forceinline__ void gemm_phase(int wid_s, LAS unsigned char* lds, const Gemm g, const Sched& S, const Epi& E) {
;     ...
;             const bool last = (t == nt - 2);
;             const char* a1 = cA + (size_t)(t + 1) * kstep;
;             const char* a2 = last ? nA : cA + (size_t)(t + 2) * kstep; const char* b2 = last ? nB : cB + (size_t)(t + 2) * kstep;
;             const char* a3 = a2 + kstep; const char* b3 = b2 + kstep;
;             if (last && has_next) S.a_ready(nxt);
;             PG8_LDB(B0, 0, 0); PG8_LDB(B1, 0, 1); PG8_SCHED; PG8_LDA(At, 0, 0); PG8_STAGE(PG8_SA(1, 1), a1 + hstep, voffA);
;             PG8_WAIT_V(8); PG8_WAIT_L(0); PG8_BAR; PG8_MMA(0, 0, At, B0); PG8_MMA(0, 1, At, B1); PG8_BAR; PG8_SCHED;
;             PG8_LDA(At, 0, 1); PG8_STAGE(PG8_SB(0, 0), b2, voffB); PG8_STAGE(PG8_SB(0, 1), b2 + hstep, voffB); PG8_STAGE(PG8_SA(0, 0), a2, voffA);
.LBB0_582:
	s_add_u32 s24, s22, 0xfffe0080
	s_addc_u32 s25, s23, -1
	s_add_i32 s50, 0, 0x10000
	s_cmp_eq_u32 s49, 4
	s_cselect_b32 s27, s15, s25
	s_cselect_b32 s26, s45, s24
	v_add_u32_e32 v141, s50, v139
	s_cselect_b32 s25, s9, s48
	s_cselect_b32 s24, s46, s47
	s_add_i32 s52, 0, 0x14000
	ds_read_b128 v[142:145], v141
	ds_read_b128 v[146:149], v141 offset:1024
	ds_read_b128 v[150:153], v141 offset:2048
	ds_read_b128 v[154:157], v141 offset:3072
	v_add_u32_e32 v141, s52, v139
	ds_read_b128 v[158:161], v141
	ds_read_b128 v[162:165], v141 offset:1024
	ds_read_b128 v[166:169], v141 offset:2048
	ds_read_b128 v[170:173], v141 offset:3072
	v_lshl_add_u64 v[194:195], s[22:23], 0, v[136:137]
	s_add_i32 m0, s21, 0xc000
	ds_read_b128 v[174:177], v140
	ds_read_b128 v[178:181], v140 offset:1024
	ds_read_b128 v[182:185], v140 offset:2048
	ds_read_b128 v[186:189], v140 offset:3072
	ds_read_b128 v[190:193], v140 offset:4096
	ds_read_b128 v[208:211], v140 offset:5120
	ds_read_b128 v[212:215], v140 offset:6144
	ds_read_b128 v[216:219], v140 offset:7168
	global_load_lds_dwordx4 v[194:195], off
	v_lshl_add_u64 v[194:195], s[22:23], 0, v[134:135]
	s_add_i32 m0, s21, 0xe000
	s_nop 0
	global_load_lds_dwordx4 v[194:195], off
	s_waitcnt vmcnt(8)
	s_waitcnt lgkmcnt(0)
	s_barrier
	v_mfma_f32_16x16x32_f16 v[128:131], v[142:145], v[174:177], v[128:131]
	v_mfma_f32_16x16x32_f16 v[120:123], v[150:153], v[174:177], v[120:123]
	v_mfma_f32_16x16x32_f16 v[112:115], v[142:145], v[182:185], v[112:115]
	v_mfma_f32_16x16x32_f16 v[104:107], v[150:153], v[182:185], v[104:107]
	v_mfma_f32_16x16x32_f16 v[96:99], v[142:145], v[190:193], v[96:99]
	v_mfma_f32_16x16x32_f16 v[88:91], v[150:153], v[190:193], v[88:91]
	v_mfma_f32_16x16x32_f16 v[80:83], v[142:145], v[212:215], v[80:83]
	v_mfma_f32_16x16x32_f16 v[72:75], v[150:153], v[212:215], v[72:75]
	v_mfma_f32_16x16x32_f16 v[128:131], v[146:149], v[178:181], v[128:131]
	v_mfma_f32_16x16x32_f16 v[120:123], v[154:157], v[178:181], v[120:123]
	v_mfma_f32_16x16x32_f16 v[112:115], v[146:149], v[186:189], v[112:115]
	v_mfma_f32_16x16x32_f16 v[104:107], v[154:157], v[186:189], v[104:107]
	v_mfma_f32_16x16x32_f16 v[96:99], v[146:149], v[208:211], v[96:99]
	v_mfma_f32_16x16x32_f16 v[88:91], v[154:157], v[208:211], v[88:91]
	v_mfma_f32_16x16x32_f16 v[80:83], v[146:149], v[216:219], v[80:83]
	v_mfma_f32_16x16x32_f16 v[72:75], v[154:157], v[216:219], v[72:75]
	v_mfma_f32_16x16x32_f16 v[124:127], v[158:161], v[174:177], v[124:127]
	v_mfma_f32_16x16x32_f16 v[116:119], v[166:169], v[174:177], v[116:119]
	v_mfma_f32_16x16x32_f16 v[108:111], v[158:161], v[182:185], v[108:111]
	v_mfma_f32_16x16x32_f16 v[100:103], v[166:169], v[182:185], v[100:103]
	v_mfma_f32_16x16x32_f16 v[92:95], v[158:161], v[190:193], v[92:95]
	v_mfma_f32_16x16x32_f16 v[84:87], v[166:169], v[190:193], v[84:87]
	v_mfma_f32_16x16x32_f16 v[76:79], v[158:161], v[212:215], v[76:79]
	v_mfma_f32_16x16x32_f16 v[68:71], v[166:169], v[212:215], v[68:71]
	v_mfma_f32_16x16x32_f16 v[124:127], v[162:165], v[178:181], v[124:127]
	v_mfma_f32_16x16x32_f16 v[116:119], v[170:173], v[178:181], v[116:119]
	v_mfma_f32_16x16x32_f16 v[108:111], v[162:165], v[186:189], v[108:111]
	v_mfma_f32_16x16x32_f16 v[100:103], v[170:173], v[186:189], v[100:103]
	v_mfma_f32_16x16x32_f16 v[92:95], v[162:165], v[208:211], v[92:95]
	v_mfma_f32_16x16x32_f16 v[84:87], v[170:173], v[208:211], v[84:87]
	v_mfma_f32_16x16x32_f16 v[76:79], v[162:165], v[216:219], v[76:79]
	v_mfma_f32_16x16x32_f16 v[68:71], v[170:173], v[216:219], v[68:71]
	s_barrier
	s_add_i32 s50, s50, s36
	v_lshl_add_u64 v[194:195], s[24:25], 0, v[0:1]
	s_mov_b32 m0, s50
	ds_read_b128 v[174:177], v140 offset:16384
	ds_read_b128 v[178:181], v140 offset:17408
	ds_read_b128 v[182:185], v140 offset:18432
	ds_read_b128 v[186:189], v140 offset:19456
	ds_read_b128 v[190:193], v140 offset:20480
	ds_read_b128 v[208:211], v140 offset:21504
	ds_read_b128 v[212:215], v140 offset:22528
	ds_read_b128 v[216:219], v140 offset:23552
	global_load_lds_dwordx4 v[194:195], off
	s_add_i32 m0, s50, 0x2000
	s_add_u32 s50, s24, 0x20000
	v_lshl_add_u64 v[220:221], s[24:25], 0, v[132:133]
	s_addc_u32 s51, s25, 0
	s_add_i32 s52, s52, s36
	global_load_lds_dwordx4 v[220:221], off
	v_lshl_add_u64 v[222:223], s[50:51], 0, v[0:1]
	s_mov_b32 m0, s52
	v_lshl_add_u64 v[224:225], s[26:27], 0, v[132:133]
	global_load_lds_dwordx4 v[222:223], off
	v_lshl_add_u64 v[222:223], s[50:51], 0, v[132:133]
	s_add_i32 m0, s52, 0x2000
	s_nop 0
	global_load_lds_dwordx4 v[222:223], off
	v_lshl_add_u64 v[222:223], s[26:27], 0, v[0:1]
	s_mov_b32 m0, s21
	s_nop 0
	global_load_lds_dwordx4 v[222:223], off
	s_mov_b32 m0, s37
	s_nop 0
	global_load_lds_dwordx4 v[224:225], off
	s_waitcnt vmcnt(8)
	s_waitcnt lgkmcnt(0)
	s_barrier
; #define PG8_STAGE(bufoff, gbase, voff) do { _Pragma("unroll") for (int _i = 0; _i < 2; ++_i) \
;         __builtin_amdgcn_global_load_lds((const unsigned*)((const char*)(gbase) + (voff)[_i]), (LAS unsigned*)(lds + (bufoff) + ldsw + _i * 8192), 16, 0, 0); } while (0)
; #define PG8_LDA(dst, b, h) do { _Pragma("unroll") for (int m = 0; m < 4; ++m) _Pragma("unroll") for (int k = 0; k < 2; ++k) dst[m][k] = *(const LAS bf16x8*)(lds + PG8_SA(b, h) + aoff + m * 2048 + k * 1024); } while (0)
; #define PG8_LDB(dst, b, h) do { _Pragma("unroll") for (int n = 0; n < 2; ++n) _Pragma("unroll") for (int k = 0; k < 2; ++k) dst[n][k] = *(const LAS bf16x8*)(lds + PG8_SB(b, h) + boff + n * 2048 + k * 1024); } while (0)
; #define PG8_WAIT_V(n) asm volatile("s_waitcnt vmcnt(" #n ")" ::: "memory")
; #define PG8_WAIT_L(n) asm volatile("s_waitcnt lgkmcnt(" #n ")" ::: "memory")
; #define PG8_BAR __builtin_amdgcn_s_barrier()
; #define PG8_SCHED __builtin_amdgcn_sched_barrier(0)
; template <class Epi, class Sched, bool FUSED = false, bool APERM = false>
; __device__ __forceinline__ void gemm_phase(int wid_s, LAS unsigned char* lds, const Gemm g, const Sched& S, const Epi& E) {
;     ...
;             PG8_WAIT_V(8); PG8_WAIT_L(0); PG8_BAR; PG8_MMA(1, 0, At, B0); PG8_MMA(1, 1, At, B1); PG8_BAR; PG8_SCHED;
;             PG8_LDB(B0, 1, 0); PG8_LDB(B1, 1, 1); PG8_SCHED; PG8_LDA(At, 1, 0); PG8_STAGE(PG8_SA(0, 1), a2 + hstep, voffA);
;             PG8_WAIT_V(8); PG8_WAIT_L(0); PG8_BAR; PG8_MMA(0, 0, At, B0); PG8_MMA(0, 1, At, B1); PG8_BAR; PG8_SCHED;
	v_mfma_f32_16x16x32_f16 v[64:67], v[142:145], v[174:177], v[64:67]
	v_mfma_f32_16x16x32_f16 v[56:59], v[150:153], v[174:177], v[56:59]
	v_mfma_f32_16x16x32_f16 v[48:51], v[142:145], v[182:185], v[48:51]
	v_mfma_f32_16x16x32_f16 v[40:43], v[150:153], v[182:185], v[40:43]
	v_mfma_f32_16x16x32_f16 v[32:35], v[142:145], v[190:193], v[32:35]
	v_mfma_f32_16x16x32_f16 v[24:27], v[150:153], v[190:193], v[24:27]
	v_mfma_f32_16x16x32_f16 v[16:19], v[142:145], v[212:215], v[16:19]
	v_mfma_f32_16x16x32_f16 v[8:11], v[150:153], v[212:215], v[8:11]
	v_mfma_f32_16x16x32_f16 v[64:67], v[146:149], v[178:181], v[64:67]
	v_mfma_f32_16x16x32_f16 v[56:59], v[154:157], v[178:181], v[56:59]
	v_mfma_f32_16x16x32_f16 v[48:51], v[146:149], v[186:189], v[48:51]
	v_mfma_f32_16x16x32_f16 v[40:43], v[154:157], v[186:189], v[40:43]
	v_mfma_f32_16x16x32_f16 v[32:35], v[146:149], v[208:211], v[32:35]
	v_mfma_f32_16x16x32_f16 v[24:27], v[154:157], v[208:211], v[24:27]
	v_mfma_f32_16x16x32_f16 v[16:19], v[146:149], v[216:219], v[16:19]
	v_mfma_f32_16x16x32_f16 v[8:11], v[154:157], v[216:219], v[8:11]
	v_mfma_f32_16x16x32_f16 v[60:63], v[158:161], v[174:177], v[60:63]
	v_mfma_f32_16x16x32_f16 v[52:55], v[166:169], v[174:177], v[52:55]
	v_mfma_f32_16x16x32_f16 v[44:47], v[158:161], v[182:185], v[44:47]
	v_mfma_f32_16x16x32_f16 v[36:39], v[166:169], v[182:185], v[36:39]
	v_mfma_f32_16x16x32_f16 v[28:31], v[158:161], v[190:193], v[28:31]
	v_mfma_f32_16x16x32_f16 v[20:23], v[166:169], v[190:193], v[20:23]
	v_mfma_f32_16x16x32_f16 v[12:15], v[158:161], v[212:215], v[12:15]
	v_mfma_f32_16x16x32_f16 v[4:7], v[166:169], v[212:215], v[4:7]
	v_mfma_f32_16x16x32_f16 v[60:63], v[162:165], v[178:181], v[60:63]
	v_mfma_f32_16x16x32_f16 v[52:55], v[170:173], v[178:181], v[52:55]
	v_mfma_f32_16x16x32_f16 v[44:47], v[162:165], v[186:189], v[44:47]
	v_mfma_f32_16x16x32_f16 v[36:39], v[170:173], v[186:189], v[36:39]
	v_mfma_f32_16x16x32_f16 v[28:31], v[162:165], v[208:211], v[28:31]
	v_mfma_f32_16x16x32_f16 v[20:23], v[170:173], v[208:211], v[20:23]
	v_mfma_f32_16x16x32_f16 v[12:15], v[162:165], v[216:219], v[12:15]
	v_mfma_f32_16x16x32_f16 v[4:7], v[170:173], v[216:219], v[4:7]
	s_barrier
	s_add_i32 s50, 0, 0x18000
	v_add_u32_e32 v141, s50, v139
	s_add_i32 s51, 0, 0x1c000
	ds_read_b128 v[142:145], v141
	ds_read_b128 v[146:149], v141 offset:1024
	ds_read_b128 v[150:153], v141 offset:2048
	ds_read_b128 v[154:157], v141 offset:3072
	v_add_u32_e32 v141, s51, v139
	ds_read_b128 v[158:161], v141
	ds_read_b128 v[162:165], v141 offset:1024
	ds_read_b128 v[166:169], v141 offset:2048
	ds_read_b128 v[170:173], v141 offset:3072
	s_add_u32 s26, s26, 0x20000
	s_addc_u32 s27, s27, 0
	s_mov_b32 m0, s38
	v_lshl_add_u64 v[226:227], s[26:27], 0, v[0:1]
	ds_read_b128 v[174:177], v140 offset:32768
	ds_read_b128 v[178:181], v140 offset:33792
	ds_read_b128 v[182:185], v140 offset:34816
	ds_read_b128 v[186:189], v140 offset:35840
	ds_read_b128 v[190:193], v140 offset:36864
	ds_read_b128 v[208:211], v140 offset:37888
	ds_read_b128 v[212:215], v140 offset:38912
	ds_read_b128 v[216:219], v140 offset:39936
	global_load_lds_dwordx4 v[226:227], off
	v_lshl_add_u64 v[226:227], s[26:27], 0, v[132:133]
	s_mov_b32 m0, s39
	s_nop 0
	global_load_lds_dwordx4 v[226:227], off
	s_waitcnt vmcnt(8)
	s_waitcnt lgkmcnt(0)
	s_barrier
	v_mfma_f32_16x16x32_f16 v[128:131], v[142:145], v[174:177], v[128:131]
	v_mfma_f32_16x16x32_f16 v[120:123], v[150:153], v[174:177], v[120:123]
	v_mfma_f32_16x16x32_f16 v[112:115], v[142:145], v[182:185], v[112:115]
	v_mfma_f32_16x16x32_f16 v[104:107], v[150:153], v[182:185], v[104:107]
	v_mfma_f32_16x16x32_f16 v[96:99], v[142:145], v[190:193], v[96:99]
	v_mfma_f32_16x16x32_f16 v[88:91], v[150:153], v[190:193], v[88:91]
	v_mfma_f32_16x16x32_f16 v[80:83], v[142:145], v[212:215], v[80:83]
	v_mfma_f32_16x16x32_f16 v[72:75], v[150:153], v[212:215], v[72:75]
	v_mfma_f32_16x16x32_f16 v[128:131], v[146:149], v[178:181], v[128:131]
	v_mfma_f32_16x16x32_f16 v[120:123], v[154:157], v[178:181], v[120:123]
	v_mfma_f32_16x16x32_f16 v[112:115], v[146:149], v[186:189], v[112:115]
	v_mfma_f32_16x16x32_f16 v[104:107], v[154:157], v[186:189], v[104:107]
	v_mfma_f32_16x16x32_f16 v[96:99], v[146:149], v[208:211], v[96:99]
	v_mfma_f32_16x16x32_f16 v[88:91], v[154:157], v[208:211], v[88:91]
	v_mfma_f32_16x16x32_f16 v[80:83], v[146:149], v[216:219], v[80:83]
	v_mfma_f32_16x16x32_f16 v[72:75], v[154:157], v[216:219], v[72:75]
	v_mfma_f32_16x16x32_f16 v[124:127], v[158:161], v[174:177], v[124:127]
	v_mfma_f32_16x16x32_f16 v[116:119], v[166:169], v[174:177], v[116:119]
	v_mfma_f32_16x16x32_f16 v[108:111], v[158:161], v[182:185], v[108:111]
	v_mfma_f32_16x16x32_f16 v[100:103], v[166:169], v[182:185], v[100:103]
	v_mfma_f32_16x16x32_f16 v[92:95], v[158:161], v[190:193], v[92:95]
	v_mfma_f32_16x16x32_f16 v[84:87], v[166:169], v[190:193], v[84:87]
	v_mfma_f32_16x16x32_f16 v[76:79], v[158:161], v[212:215], v[76:79]
	v_mfma_f32_16x16x32_f16 v[68:71], v[166:169], v[212:215], v[68:71]
	v_mfma_f32_16x16x32_f16 v[124:127], v[162:165], v[178:181], v[124:127]
	v_mfma_f32_16x16x32_f16 v[116:119], v[170:173], v[178:181], v[116:119]
	v_mfma_f32_16x16x32_f16 v[108:111], v[162:165], v[186:189], v[108:111]
	v_mfma_f32_16x16x32_f16 v[100:103], v[170:173], v[186:189], v[100:103]
	v_mfma_f32_16x16x32_f16 v[92:95], v[162:165], v[208:211], v[92:95]
	v_mfma_f32_16x16x32_f16 v[84:87], v[170:173], v[208:211], v[84:87]
	v_mfma_f32_16x16x32_f16 v[76:79], v[162:165], v[216:219], v[76:79]
	v_mfma_f32_16x16x32_f16 v[68:71], v[170:173], v[216:219], v[68:71]
	s_barrier
; #define PG8_STAGE(bufoff, gbase, voff) do { _Pragma("unroll") for (int _i = 0; _i < 2; ++_i) \
;         __builtin_amdgcn_global_load_lds((const unsigned*)((const char*)(gbase) + (voff)[_i]), (LAS unsigned*)(lds + (bufoff) + ldsw + _i * 8192), 16, 0, 0); } while (0)
; #define PG8_LDA(dst, b, h) do { _Pragma("unroll") for (int m = 0; m < 4; ++m) _Pragma("unroll") for (int k = 0; k < 2; ++k) dst[m][k] = *(const LAS bf16x8*)(lds + PG8_SA(b, h) + aoff + m * 2048 + k * 1024); } while (0)
; #define PG8_WAIT_V(n) asm volatile("s_waitcnt vmcnt(" #n ")" ::: "memory")
; #define PG8_WAIT_L(n) asm volatile("s_waitcnt lgkmcnt(" #n ")" ::: "memory")
; #define PG8_BAR __builtin_amdgcn_s_barrier()
; #define PG8_SCHED __builtin_amdgcn_sched_barrier(0)
; template <class Epi, class Sched, bool FUSED = false, bool APERM = false>
; __device__ __forceinline__ void gemm_phase(int wid_s, LAS unsigned char* lds, const Gemm g, const Sched& S, const Epi& E) {
;     ...
;             PG8_LDA(At, 1, 1); PG8_STAGE(PG8_SB(1, 0), b3, voffB); PG8_STAGE(PG8_SB(1, 1), b3 + hstep, voffB); PG8_STAGE(PG8_SA(1, 0), a3, voffA);
;             PG8_WAIT_V(8); PG8_WAIT_L(0); PG8_BAR; PG8_MMA(1, 0, At, B0); PG8_MMA(1, 1, At, B1); PG8_BAR; PG8_SCHED;
;         }
;         if (wr == 0) PG8_BAR;
	s_add_i32 s26, s50, s36
	v_lshl_add_u64 v[194:195], v[194:195], 0, s[12:13]
	s_mov_b32 m0, s26
	ds_read_b128 v[174:177], v140 offset:49152
	ds_read_b128 v[178:181], v140 offset:50176
	ds_read_b128 v[182:185], v140 offset:51200
	ds_read_b128 v[186:189], v140 offset:52224
	ds_read_b128 v[190:193], v140 offset:53248
	ds_read_b128 v[208:211], v140 offset:54272
	ds_read_b128 v[212:215], v140 offset:55296
	ds_read_b128 v[216:219], v140 offset:56320
	global_load_lds_dwordx4 v[194:195], off
	s_add_i32 m0, s26, 0x2000
	s_add_u32 s24, s24, 0x20080
	v_lshl_add_u64 v[194:195], v[220:221], 0, s[12:13]
	s_addc_u32 s25, s25, 0
	s_add_i32 s26, s51, s36
	global_load_lds_dwordx4 v[194:195], off
	v_lshl_add_u64 v[194:195], s[24:25], 0, v[0:1]
	s_mov_b32 m0, s26
	s_nop 0
	global_load_lds_dwordx4 v[194:195], off
	v_lshl_add_u64 v[194:195], s[24:25], 0, v[132:133]
	s_add_i32 m0, s26, 0x2000
	s_nop 0
	global_load_lds_dwordx4 v[194:195], off
	v_lshl_add_u64 v[194:195], v[222:223], 0, s[12:13]
	s_mov_b32 m0, s41
	s_nop 0
	global_load_lds_dwordx4 v[194:195], off
	v_lshl_add_u64 v[194:195], v[224:225], 0, s[12:13]
	s_mov_b32 m0, s42
	s_nop 0
	global_load_lds_dwordx4 v[194:195], off
	s_waitcnt vmcnt(8)
	s_waitcnt lgkmcnt(0)
	s_barrier
	v_mfma_f32_16x16x32_f16 v[64:67], v[142:145], v[174:177], v[64:67]
	v_mfma_f32_16x16x32_f16 v[56:59], v[150:153], v[174:177], v[56:59]
	v_mfma_f32_16x16x32_f16 v[48:51], v[142:145], v[182:185], v[48:51]
	v_mfma_f32_16x16x32_f16 v[40:43], v[150:153], v[182:185], v[40:43]
	v_mfma_f32_16x16x32_f16 v[32:35], v[142:145], v[190:193], v[32:35]
	v_mfma_f32_16x16x32_f16 v[24:27], v[150:153], v[190:193], v[24:27]
	v_mfma_f32_16x16x32_f16 v[16:19], v[142:145], v[212:215], v[16:19]
	v_mfma_f32_16x16x32_f16 v[8:11], v[150:153], v[212:215], v[8:11]
	v_mfma_f32_16x16x32_f16 v[64:67], v[146:149], v[178:181], v[64:67]
	v_mfma_f32_16x16x32_f16 v[56:59], v[154:157], v[178:181], v[56:59]
	v_mfma_f32_16x16x32_f16 v[48:51], v[146:149], v[186:189], v[48:51]
	v_mfma_f32_16x16x32_f16 v[40:43], v[154:157], v[186:189], v[40:43]
	v_mfma_f32_16x16x32_f16 v[32:35], v[146:149], v[208:211], v[32:35]
	v_mfma_f32_16x16x32_f16 v[24:27], v[154:157], v[208:211], v[24:27]
	v_mfma_f32_16x16x32_f16 v[16:19], v[146:149], v[216:219], v[16:19]
	v_mfma_f32_16x16x32_f16 v[8:11], v[154:157], v[216:219], v[8:11]
	v_mfma_f32_16x16x32_f16 v[60:63], v[158:161], v[174:177], v[60:63]
	v_mfma_f32_16x16x32_f16 v[52:55], v[166:169], v[174:177], v[52:55]
	v_mfma_f32_16x16x32_f16 v[44:47], v[158:161], v[182:185], v[44:47]
	v_mfma_f32_16x16x32_f16 v[36:39], v[166:169], v[182:185], v[36:39]
	v_mfma_f32_16x16x32_f16 v[28:31], v[158:161], v[190:193], v[28:31]
	v_mfma_f32_16x16x32_f16 v[20:23], v[166:169], v[190:193], v[20:23]
	v_mfma_f32_16x16x32_f16 v[12:15], v[158:161], v[212:215], v[12:15]
	v_mfma_f32_16x16x32_f16 v[4:7], v[166:169], v[212:215], v[4:7]
	v_mfma_f32_16x16x32_f16 v[60:63], v[162:165], v[178:181], v[60:63]
	v_mfma_f32_16x16x32_f16 v[52:55], v[170:173], v[178:181], v[52:55]
	v_mfma_f32_16x16x32_f16 v[44:47], v[162:165], v[186:189], v[44:47]
	v_mfma_f32_16x16x32_f16 v[36:39], v[170:173], v[186:189], v[36:39]
	v_mfma_f32_16x16x32_f16 v[28:31], v[162:165], v[208:211], v[28:31]
	v_mfma_f32_16x16x32_f16 v[20:23], v[170:173], v[208:211], v[20:23]
	v_mfma_f32_16x16x32_f16 v[12:15], v[162:165], v[216:219], v[12:15]
	v_mfma_f32_16x16x32_f16 v[4:7], v[170:173], v[216:219], v[4:7]
	s_barrier
	s_add_i32 s49, s49, 2
	s_add_u32 s47, s47, 0x100
	s_addc_u32 s48, s48, 0
	s_add_u32 s22, s22, 0x100
	s_addc_u32 s23, s23, 0
	s_cmp_gt_u32 s49, 5
	s_cbranch_scc0 .LBB0_582
	s_and_b64 vcc, exec, s[6:7]
	s_cbranch_vccz .LBB0_585
	s_barrier

; #define PG8_STAGE(bufoff, gbase, voff) do { _Pragma("unroll") for (int _i = 0; _i < 2; ++_i) \
;         __builtin_amdgcn_global_load_lds((const unsigned*)((const char*)(gbase) + (voff)[_i]), (LAS unsigned*)(lds + (bufoff) + ldsw + _i * 8192), 16, 0, 0); } while (0)
; #define PG8_LDA(dst, b, h) do { _Pragma("unroll") for (int m = 0; m < 4; ++m) _Pragma("unroll") for (int k = 0; k < 2; ++k) dst[m][k] = *(const LAS bf16x8*)(lds + PG8_SA(b, h) + aoff + m * 2048 + k * 1024); } while (0)
; #define PG8_LDB(dst, b, h) do { _Pragma("unroll") for (int n = 0; n < 2; ++n) _Pragma("unroll") for (int k = 0; k < 2; ++k) dst[n][k] = *(const LAS bf16x8*)(lds + PG8_SB(b, h) + boff + n * 2048 + k * 1024); } while (0)
; #define PG8_WAIT_V(n) asm volatile("s_waitcnt vmcnt(" #n ")" ::: "memory")
; #define PG8_WAIT_L(n) asm volatile("s_waitcnt lgkmcnt(" #n ")" ::: "memory")
; #define PG8_BAR __builtin_amdgcn_s_barrier()
; #define PG8_SCHED __builtin_amdgcn_sched_barrier(0)
; template <class Epi, class Sched, bool FUSED = false, bool APERM = false>
; __device__ __forceinline__ void gemm_phase(int wid_s, LAS unsigned char* lds, const Gemm g, const Sched& S, const Epi& E) {
;     ...
;             const bool last = (t == nt - 2);
;             const char* a1 = cA + (size_t)(t + 1) * kstep;
;             const char* a2 = last ? nA : cA + (size_t)(t + 2) * kstep; const char* b2 = last ? nB : cB + (size_t)(t + 2) * kstep;
;             const char* a3 = a2 + kstep; const char* b3 = b2 + kstep;
;             if (last && has_next) S.a_ready(nxt);
;             PG8_LDB(B0, 0, 0); PG8_LDB(B1, 0, 1); PG8_SCHED; PG8_LDA(At, 0, 0); PG8_STAGE(PG8_SA(1, 1), a1 + hstep, voffA);
;             PG8_WAIT_V(8); PG8_WAIT_L(0); PG8_BAR; PG8_MMA(0, 0, At, B0); PG8_MMA(0, 1, At, B1); PG8_BAR; PG8_SCHED;
;             PG8_LDA(At, 0, 1); PG8_STAGE(PG8_SB(0, 0), b2, voffB); PG8_STAGE(PG8_SB(0, 1), b2 + hstep, voffB); PG8_STAGE(PG8_SA(0, 0), a2, voffA);
;             PG8_WAIT_V(8); PG8_WAIT_L(0); PG8_BAR; PG8_MMA(1, 0, At, B0); PG8_MMA(1, 1, At, B1); PG8_BAR; PG8_SCHED;
.LBB0_653:
	s_add_u32 s38, s28, s36
	s_addc_u32 s39, s29, s37
	s_add_u32 s38, s38, 0x100
	s_addc_u32 s39, s39, 0
	s_add_u32 s63, s58, s36
	s_addc_u32 s64, s59, s37
	s_add_i32 s65, 0, 0x10000
	s_cmpk_eq_i32 s36, 0xf00
	s_cselect_b32 s41, s27, s39
	s_cselect_b32 s40, s60, s38
	v_add_u32_e32 v143, s65, v3
	s_cselect_b32 s39, s25, s64
	s_cselect_b32 s38, s61, s63
	s_add_i32 s63, 0, 0x14000
	ds_read_b128 v[144:147], v143
	ds_read_b128 v[148:151], v143 offset:1024
	ds_read_b128 v[152:155], v143 offset:2048
	ds_read_b128 v[156:159], v143 offset:3072
	v_add_u32_e32 v143, s63, v3
	ds_read_b128 v[160:163], v143
	ds_read_b128 v[164:167], v143 offset:1024
	ds_read_b128 v[168:171], v143 offset:2048
	ds_read_b128 v[172:175], v143 offset:3072
	v_lshl_add_u64 v[222:223], v[140:141], 0, s[36:37]
	s_add_i32 m0, s15, 0xc000
	ds_read_b128 v[176:179], v142
	ds_read_b128 v[180:183], v142 offset:1024
	ds_read_b128 v[184:187], v142 offset:2048
	ds_read_b128 v[188:191], v142 offset:3072
	ds_read_b128 v[192:195], v142 offset:4096
	ds_read_b128 v[208:211], v142 offset:5120
	ds_read_b128 v[212:215], v142 offset:6144
	ds_read_b128 v[216:219], v142 offset:7168
	global_load_lds_dwordx4 v[222:223], off
	v_lshl_add_u64 v[222:223], v[138:139], 0, s[36:37]
	s_add_i32 m0, s15, 0xe000
	s_nop 0
	global_load_lds_dwordx4 v[222:223], off
	s_waitcnt vmcnt(8)
	s_waitcnt lgkmcnt(0)
	s_barrier
	v_mfma_f32_16x16x32_f16 v[128:131], v[144:147], v[176:179], v[128:131]
	v_mfma_f32_16x16x32_f16 v[124:127], v[152:155], v[176:179], v[124:127]
	v_mfma_f32_16x16x32_f16 v[112:115], v[144:147], v[184:187], v[112:115]
	v_mfma_f32_16x16x32_f16 v[108:111], v[152:155], v[184:187], v[108:111]
	v_mfma_f32_16x16x32_f16 v[96:99], v[144:147], v[192:195], v[96:99]
	v_mfma_f32_16x16x32_f16 v[92:95], v[152:155], v[192:195], v[92:95]
	v_mfma_f32_16x16x32_f16 v[80:83], v[144:147], v[212:215], v[80:83]
	v_mfma_f32_16x16x32_f16 v[76:79], v[152:155], v[212:215], v[76:79]
	v_mfma_f32_16x16x32_f16 v[128:131], v[148:151], v[180:183], v[128:131]
	v_mfma_f32_16x16x32_f16 v[124:127], v[156:159], v[180:183], v[124:127]
	v_mfma_f32_16x16x32_f16 v[112:115], v[148:151], v[188:191], v[112:115]
	v_mfma_f32_16x16x32_f16 v[108:111], v[156:159], v[188:191], v[108:111]
	v_mfma_f32_16x16x32_f16 v[96:99], v[148:151], v[208:211], v[96:99]
	v_mfma_f32_16x16x32_f16 v[92:95], v[156:159], v[208:211], v[92:95]
	v_mfma_f32_16x16x32_f16 v[80:83], v[148:151], v[216:219], v[80:83]
	v_mfma_f32_16x16x32_f16 v[76:79], v[156:159], v[216:219], v[76:79]
	v_mfma_f32_16x16x32_f16 v[120:123], v[160:163], v[176:179], v[120:123]
	v_mfma_f32_16x16x32_f16 v[116:119], v[168:171], v[176:179], v[116:119]
	v_mfma_f32_16x16x32_f16 v[104:107], v[160:163], v[184:187], v[104:107]
	v_mfma_f32_16x16x32_f16 v[100:103], v[168:171], v[184:187], v[100:103]
	v_mfma_f32_16x16x32_f16 v[88:91], v[160:163], v[192:195], v[88:91]
	v_mfma_f32_16x16x32_f16 v[84:87], v[168:171], v[192:195], v[84:87]
	v_mfma_f32_16x16x32_f16 v[72:75], v[160:163], v[212:215], v[72:75]
	v_mfma_f32_16x16x32_f16 v[68:71], v[168:171], v[212:215], v[68:71]
	v_mfma_f32_16x16x32_f16 v[120:123], v[164:167], v[180:183], v[120:123]
	v_mfma_f32_16x16x32_f16 v[116:119], v[172:175], v[180:183], v[116:119]
	v_mfma_f32_16x16x32_f16 v[104:107], v[164:167], v[188:191], v[104:107]
	v_mfma_f32_16x16x32_f16 v[100:103], v[172:175], v[188:191], v[100:103]
	v_mfma_f32_16x16x32_f16 v[88:91], v[164:167], v[208:211], v[88:91]
	v_mfma_f32_16x16x32_f16 v[84:87], v[172:175], v[208:211], v[84:87]
	v_mfma_f32_16x16x32_f16 v[72:75], v[164:167], v[216:219], v[72:75]
	v_mfma_f32_16x16x32_f16 v[68:71], v[172:175], v[216:219], v[68:71]
	s_barrier
	s_add_i32 s64, s65, s49
	v_lshl_add_u64 v[222:223], s[38:39], 0, v[0:1]
	s_mov_b32 m0, s64
	ds_read_b128 v[176:179], v142 offset:16384
	ds_read_b128 v[180:183], v142 offset:17408
	ds_read_b128 v[184:187], v142 offset:18432
	ds_read_b128 v[188:191], v142 offset:19456
	ds_read_b128 v[192:195], v142 offset:20480
	ds_read_b128 v[208:211], v142 offset:21504
	ds_read_b128 v[212:215], v142 offset:22528
	ds_read_b128 v[216:219], v142 offset:23552
	global_load_lds_dwordx4 v[222:223], off
	s_add_i32 m0, s64, 0x2000
	s_add_u32 s64, s38, 0x80000
	v_lshl_add_u64 v[224:225], s[38:39], 0, v[132:133]
	s_addc_u32 s65, s39, 0
	s_add_i32 s63, s63, s49
	global_load_lds_dwordx4 v[224:225], off
	v_lshl_add_u64 v[226:227], s[64:65], 0, v[0:1]
	s_mov_b32 m0, s63
	v_lshl_add_u64 v[228:229], s[40:41], 0, v[132:133]
	global_load_lds_dwordx4 v[226:227], off
	v_lshl_add_u64 v[226:227], s[64:65], 0, v[132:133]
	s_add_i32 m0, s63, 0x2000
	s_nop 0
	global_load_lds_dwordx4 v[226:227], off
	v_lshl_add_u64 v[226:227], s[40:41], 0, v[0:1]
	s_mov_b32 m0, s15
	s_nop 0
	global_load_lds_dwordx4 v[226:227], off
	s_mov_b32 m0, s50
	s_nop 0
	global_load_lds_dwordx4 v[228:229], off
	s_waitcnt vmcnt(8)
	s_waitcnt lgkmcnt(0)
	s_barrier
; #define PG8_STAGE(bufoff, gbase, voff) do { _Pragma("unroll") for (int _i = 0; _i < 2; ++_i) \
;         __builtin_amdgcn_global_load_lds((const unsigned*)((const char*)(gbase) + (voff)[_i]), (LAS unsigned*)(lds + (bufoff) + ldsw + _i * 8192), 16, 0, 0); } while (0)
; #define PG8_LDA(dst, b, h) do { _Pragma("unroll") for (int m = 0; m < 4; ++m) _Pragma("unroll") for (int k = 0; k < 2; ++k) dst[m][k] = *(const LAS bf16x8*)(lds + PG8_SA(b, h) + aoff + m * 2048 + k * 1024); } while (0)
; #define PG8_LDB(dst, b, h) do { _Pragma("unroll") for (int n = 0; n < 2; ++n) _Pragma("unroll") for (int k = 0; k < 2; ++k) dst[n][k] = *(const LAS bf16x8*)(lds + PG8_SB(b, h) + boff + n * 2048 + k * 1024); } while (0)
; #define PG8_WAIT_V(n) asm volatile("s_waitcnt vmcnt(" #n ")" ::: "memory")
; #define PG8_WAIT_L(n) asm volatile("s_waitcnt lgkmcnt(" #n ")" ::: "memory")
; #define PG8_BAR __builtin_amdgcn_s_barrier()
; #define PG8_SCHED __builtin_amdgcn_sched_barrier(0)
; template <class Epi, class Sched, bool FUSED = false, bool APERM = false>
; __device__ __forceinline__ void gemm_phase(int wid_s, LAS unsigned char* lds, const Gemm g, const Sched& S, const Epi& E) {
;     ...
;             PG8_WAIT_V(8); PG8_WAIT_L(0); PG8_BAR; PG8_MMA(1, 0, At, B0); PG8_MMA(1, 1, At, B1); PG8_BAR; PG8_SCHED;
;             PG8_LDB(B0, 1, 0); PG8_LDB(B1, 1, 1); PG8_SCHED; PG8_LDA(At, 1, 0); PG8_STAGE(PG8_SA(0, 1), a2 + hstep, voffA);
;             PG8_WAIT_V(8); PG8_WAIT_L(0); PG8_BAR; PG8_MMA(0, 0, At, B0); PG8_MMA(0, 1, At, B1); PG8_BAR; PG8_SCHED;
	v_mfma_f32_16x16x32_f16 v[64:67], v[144:147], v[176:179], v[64:67]
	v_mfma_f32_16x16x32_f16 v[60:63], v[152:155], v[176:179], v[60:63]
	v_mfma_f32_16x16x32_f16 v[48:51], v[144:147], v[184:187], v[48:51]
	v_mfma_f32_16x16x32_f16 v[44:47], v[152:155], v[184:187], v[44:47]
	v_mfma_f32_16x16x32_f16 v[32:35], v[144:147], v[192:195], v[32:35]
	v_mfma_f32_16x16x32_f16 v[28:31], v[152:155], v[192:195], v[28:31]
	v_mfma_f32_16x16x32_f16 v[16:19], v[144:147], v[212:215], v[16:19]
	v_mfma_f32_16x16x32_f16 v[12:15], v[152:155], v[212:215], v[12:15]
	v_mfma_f32_16x16x32_f16 v[64:67], v[148:151], v[180:183], v[64:67]
	v_mfma_f32_16x16x32_f16 v[60:63], v[156:159], v[180:183], v[60:63]
	v_mfma_f32_16x16x32_f16 v[48:51], v[148:151], v[188:191], v[48:51]
	v_mfma_f32_16x16x32_f16 v[44:47], v[156:159], v[188:191], v[44:47]
	v_mfma_f32_16x16x32_f16 v[32:35], v[148:151], v[208:211], v[32:35]
	v_mfma_f32_16x16x32_f16 v[28:31], v[156:159], v[208:211], v[28:31]
	v_mfma_f32_16x16x32_f16 v[16:19], v[148:151], v[216:219], v[16:19]
	v_mfma_f32_16x16x32_f16 v[12:15], v[156:159], v[216:219], v[12:15]
	v_mfma_f32_16x16x32_f16 v[56:59], v[160:163], v[176:179], v[56:59]
	v_mfma_f32_16x16x32_f16 v[52:55], v[168:171], v[176:179], v[52:55]
	v_mfma_f32_16x16x32_f16 v[40:43], v[160:163], v[184:187], v[40:43]
	v_mfma_f32_16x16x32_f16 v[36:39], v[168:171], v[184:187], v[36:39]
	v_mfma_f32_16x16x32_f16 v[24:27], v[160:163], v[192:195], v[24:27]
	v_mfma_f32_16x16x32_f16 v[20:23], v[168:171], v[192:195], v[20:23]
	v_mfma_f32_16x16x32_f16 v[8:11], v[160:163], v[212:215], v[8:11]
	v_mfma_f32_16x16x32_f16 v[4:7], v[168:171], v[212:215], v[4:7]
	v_mfma_f32_16x16x32_f16 v[56:59], v[164:167], v[180:183], v[56:59]
	v_mfma_f32_16x16x32_f16 v[52:55], v[172:175], v[180:183], v[52:55]
	v_mfma_f32_16x16x32_f16 v[40:43], v[164:167], v[188:191], v[40:43]
	v_mfma_f32_16x16x32_f16 v[36:39], v[172:175], v[188:191], v[36:39]
	v_mfma_f32_16x16x32_f16 v[24:27], v[164:167], v[208:211], v[24:27]
	v_mfma_f32_16x16x32_f16 v[20:23], v[172:175], v[208:211], v[20:23]
	v_mfma_f32_16x16x32_f16 v[8:11], v[164:167], v[216:219], v[8:11]
	v_mfma_f32_16x16x32_f16 v[4:7], v[172:175], v[216:219], v[4:7]
	s_barrier
	s_add_i32 s63, 0, 0x18000
	v_add_u32_e32 v143, s63, v3
	s_add_i32 s64, 0, 0x1c000
	ds_read_b128 v[144:147], v143
	ds_read_b128 v[148:151], v143 offset:1024
	ds_read_b128 v[152:155], v143 offset:2048
	ds_read_b128 v[156:159], v143 offset:3072
	v_add_u32_e32 v143, s64, v3
	ds_read_b128 v[160:163], v143
	ds_read_b128 v[164:167], v143 offset:1024
	ds_read_b128 v[168:171], v143 offset:2048
	ds_read_b128 v[172:175], v143 offset:3072
	s_add_u32 s40, s40, 0x80000
	s_addc_u32 s41, s41, 0
	s_mov_b32 m0, s51
	v_lshl_add_u64 v[230:231], s[40:41], 0, v[0:1]
	ds_read_b128 v[176:179], v142 offset:32768
	ds_read_b128 v[180:183], v142 offset:33792
	ds_read_b128 v[184:187], v142 offset:34816
	ds_read_b128 v[188:191], v142 offset:35840
	ds_read_b128 v[192:195], v142 offset:36864
	ds_read_b128 v[208:211], v142 offset:37888
	ds_read_b128 v[212:215], v142 offset:38912
	ds_read_b128 v[216:219], v142 offset:39936
	global_load_lds_dwordx4 v[230:231], off
	v_lshl_add_u64 v[230:231], s[40:41], 0, v[132:133]
	s_mov_b32 m0, s52
	s_nop 0
	global_load_lds_dwordx4 v[230:231], off
	s_waitcnt vmcnt(8)
	s_waitcnt lgkmcnt(0)
	s_barrier
	v_mfma_f32_16x16x32_f16 v[128:131], v[144:147], v[176:179], v[128:131]
	v_mfma_f32_16x16x32_f16 v[124:127], v[152:155], v[176:179], v[124:127]
	v_mfma_f32_16x16x32_f16 v[112:115], v[144:147], v[184:187], v[112:115]
	v_mfma_f32_16x16x32_f16 v[108:111], v[152:155], v[184:187], v[108:111]
	v_mfma_f32_16x16x32_f16 v[96:99], v[144:147], v[192:195], v[96:99]
	v_mfma_f32_16x16x32_f16 v[92:95], v[152:155], v[192:195], v[92:95]
	v_mfma_f32_16x16x32_f16 v[80:83], v[144:147], v[212:215], v[80:83]
	v_mfma_f32_16x16x32_f16 v[76:79], v[152:155], v[212:215], v[76:79]
	v_mfma_f32_16x16x32_f16 v[128:131], v[148:151], v[180:183], v[128:131]
	v_mfma_f32_16x16x32_f16 v[124:127], v[156:159], v[180:183], v[124:127]
	v_mfma_f32_16x16x32_f16 v[112:115], v[148:151], v[188:191], v[112:115]
	v_mfma_f32_16x16x32_f16 v[108:111], v[156:159], v[188:191], v[108:111]
	v_mfma_f32_16x16x32_f16 v[96:99], v[148:151], v[208:211], v[96:99]
	v_mfma_f32_16x16x32_f16 v[92:95], v[156:159], v[208:211], v[92:95]
	v_mfma_f32_16x16x32_f16 v[80:83], v[148:151], v[216:219], v[80:83]
	v_mfma_f32_16x16x32_f16 v[76:79], v[156:159], v[216:219], v[76:79]
	v_mfma_f32_16x16x32_f16 v[120:123], v[160:163], v[176:179], v[120:123]
	v_mfma_f32_16x16x32_f16 v[116:119], v[168:171], v[176:179], v[116:119]
	v_mfma_f32_16x16x32_f16 v[104:107], v[160:163], v[184:187], v[104:107]
	v_mfma_f32_16x16x32_f16 v[100:103], v[168:171], v[184:187], v[100:103]
	v_mfma_f32_16x16x32_f16 v[88:91], v[160:163], v[192:195], v[88:91]
	v_mfma_f32_16x16x32_f16 v[84:87], v[168:171], v[192:195], v[84:87]
	v_mfma_f32_16x16x32_f16 v[72:75], v[160:163], v[212:215], v[72:75]
	v_mfma_f32_16x16x32_f16 v[68:71], v[168:171], v[212:215], v[68:71]
	v_mfma_f32_16x16x32_f16 v[120:123], v[164:167], v[180:183], v[120:123]
	v_mfma_f32_16x16x32_f16 v[116:119], v[172:175], v[180:183], v[116:119]
	v_mfma_f32_16x16x32_f16 v[104:107], v[164:167], v[188:191], v[104:107]
	v_mfma_f32_16x16x32_f16 v[100:103], v[172:175], v[188:191], v[100:103]
	v_mfma_f32_16x16x32_f16 v[88:91], v[164:167], v[208:211], v[88:91]
	v_mfma_f32_16x16x32_f16 v[84:87], v[172:175], v[208:211], v[84:87]
	v_mfma_f32_16x16x32_f16 v[72:75], v[164:167], v[216:219], v[72:75]
	v_mfma_f32_16x16x32_f16 v[68:71], v[172:175], v[216:219], v[68:71]
	s_barrier
; #define PG8_STAGE(bufoff, gbase, voff) do { _Pragma("unroll") for (int _i = 0; _i < 2; ++_i) \
;         __builtin_amdgcn_global_load_lds((const unsigned*)((const char*)(gbase) + (voff)[_i]), (LAS unsigned*)(lds + (bufoff) + ldsw + _i * 8192), 16, 0, 0); } while (0)
; #define PG8_LDA(dst, b, h) do { _Pragma("unroll") for (int m = 0; m < 4; ++m) _Pragma("unroll") for (int k = 0; k < 2; ++k) dst[m][k] = *(const LAS bf16x8*)(lds + PG8_SA(b, h) + aoff + m * 2048 + k * 1024); } while (0)
; #define PG8_WAIT_V(n) asm volatile("s_waitcnt vmcnt(" #n ")" ::: "memory")
; #define PG8_WAIT_L(n) asm volatile("s_waitcnt lgkmcnt(" #n ")" ::: "memory")
; #define PG8_BAR __builtin_amdgcn_s_barrier()
; #define PG8_SCHED __builtin_amdgcn_sched_barrier(0)
; template <class Epi, class Sched, bool FUSED = false, bool APERM = false>
; __device__ __forceinline__ void gemm_phase(int wid_s, LAS unsigned char* lds, const Gemm g, const Sched& S, const Epi& E) {
;     ...
;             PG8_LDA(At, 1, 1); PG8_STAGE(PG8_SB(1, 0), b3, voffB); PG8_STAGE(PG8_SB(1, 1), b3 + hstep, voffB); PG8_STAGE(PG8_SA(1, 0), a3, voffA);
;             PG8_WAIT_V(8); PG8_WAIT_L(0); PG8_BAR; PG8_MMA(1, 0, At, B0); PG8_MMA(1, 1, At, B1); PG8_BAR; PG8_SCHED;
;         }
;         if (wr == 0) PG8_BAR;
	s_add_i32 s40, s63, s49
	v_lshl_add_u64 v[222:223], v[222:223], 0, s[12:13]
	s_mov_b32 m0, s40
	ds_read_b128 v[176:179], v142 offset:49152
	ds_read_b128 v[180:183], v142 offset:50176
	ds_read_b128 v[184:187], v142 offset:51200
	ds_read_b128 v[188:191], v142 offset:52224
	ds_read_b128 v[192:195], v142 offset:53248
	ds_read_b128 v[208:211], v142 offset:54272
	ds_read_b128 v[212:215], v142 offset:55296
	ds_read_b128 v[216:219], v142 offset:56320
	global_load_lds_dwordx4 v[222:223], off
	s_add_i32 m0, s40, 0x2000
	s_add_u32 s38, s38, 0x80080
	v_lshl_add_u64 v[222:223], v[224:225], 0, s[12:13]
	s_addc_u32 s39, s39, 0
	s_add_i32 s40, s64, s49
	global_load_lds_dwordx4 v[222:223], off
	v_lshl_add_u64 v[222:223], s[38:39], 0, v[0:1]
	s_mov_b32 m0, s40
	s_nop 0
	global_load_lds_dwordx4 v[222:223], off
	v_lshl_add_u64 v[222:223], s[38:39], 0, v[132:133]
	s_add_i32 m0, s40, 0x2000
	s_nop 0
	global_load_lds_dwordx4 v[222:223], off
	v_lshl_add_u64 v[222:223], v[226:227], 0, s[12:13]
	s_mov_b32 m0, s54
	s_nop 0
	global_load_lds_dwordx4 v[222:223], off
	v_lshl_add_u64 v[222:223], v[228:229], 0, s[12:13]
	s_mov_b32 m0, s55
	s_nop 0
	global_load_lds_dwordx4 v[222:223], off
	s_waitcnt vmcnt(8)
	s_waitcnt lgkmcnt(0)
	s_barrier
	v_mfma_f32_16x16x32_f16 v[64:67], v[144:147], v[176:179], v[64:67]
	v_mfma_f32_16x16x32_f16 v[60:63], v[152:155], v[176:179], v[60:63]
	v_mfma_f32_16x16x32_f16 v[48:51], v[144:147], v[184:187], v[48:51]
	v_mfma_f32_16x16x32_f16 v[44:47], v[152:155], v[184:187], v[44:47]
	v_mfma_f32_16x16x32_f16 v[32:35], v[144:147], v[192:195], v[32:35]
	v_mfma_f32_16x16x32_f16 v[28:31], v[152:155], v[192:195], v[28:31]
	v_mfma_f32_16x16x32_f16 v[16:19], v[144:147], v[212:215], v[16:19]
	v_mfma_f32_16x16x32_f16 v[12:15], v[152:155], v[212:215], v[12:15]
	v_mfma_f32_16x16x32_f16 v[64:67], v[148:151], v[180:183], v[64:67]
	v_mfma_f32_16x16x32_f16 v[60:63], v[156:159], v[180:183], v[60:63]
	v_mfma_f32_16x16x32_f16 v[48:51], v[148:151], v[188:191], v[48:51]
	v_mfma_f32_16x16x32_f16 v[44:47], v[156:159], v[188:191], v[44:47]
	v_mfma_f32_16x16x32_f16 v[32:35], v[148:151], v[208:211], v[32:35]
	v_mfma_f32_16x16x32_f16 v[28:31], v[156:159], v[208:211], v[28:31]
	v_mfma_f32_16x16x32_f16 v[16:19], v[148:151], v[216:219], v[16:19]
	v_mfma_f32_16x16x32_f16 v[12:15], v[156:159], v[216:219], v[12:15]
	v_mfma_f32_16x16x32_f16 v[56:59], v[160:163], v[176:179], v[56:59]
	v_mfma_f32_16x16x32_f16 v[52:55], v[168:171], v[176:179], v[52:55]
	v_mfma_f32_16x16x32_f16 v[40:43], v[160:163], v[184:187], v[40:43]
	v_mfma_f32_16x16x32_f16 v[36:39], v[168:171], v[184:187], v[36:39]
	v_mfma_f32_16x16x32_f16 v[24:27], v[160:163], v[192:195], v[24:27]
	v_mfma_f32_16x16x32_f16 v[20:23], v[168:171], v[192:195], v[20:23]
	v_mfma_f32_16x16x32_f16 v[8:11], v[160:163], v[212:215], v[8:11]
	v_mfma_f32_16x16x32_f16 v[4:7], v[168:171], v[212:215], v[4:7]
	v_mfma_f32_16x16x32_f16 v[56:59], v[164:167], v[180:183], v[56:59]
	v_mfma_f32_16x16x32_f16 v[52:55], v[172:175], v[180:183], v[52:55]
	v_mfma_f32_16x16x32_f16 v[40:43], v[164:167], v[188:191], v[40:43]
	v_mfma_f32_16x16x32_f16 v[36:39], v[172:175], v[188:191], v[36:39]
	v_mfma_f32_16x16x32_f16 v[24:27], v[164:167], v[208:211], v[24:27]
	v_mfma_f32_16x16x32_f16 v[20:23], v[172:175], v[208:211], v[20:23]
	v_mfma_f32_16x16x32_f16 v[8:11], v[164:167], v[216:219], v[8:11]
	v_mfma_f32_16x16x32_f16 v[4:7], v[172:175], v[216:219], v[4:7]
	s_barrier
	s_add_i32 s62, s62, 2
	s_add_u32 s36, s36, 0x100
	s_addc_u32 s37, s37, 0
	s_cmp_gt_u32 s62, 29
	s_cbranch_scc0 .LBB0_653
	s_and_b64 vcc, exec, s[22:23]
	s_cbranch_vccz .LBB0_656
	s_barrier

; #define PG8_STAGE(bufoff, gbase, voff) do { _Pragma("unroll") for (int _i = 0; _i < 2; ++_i) \
;         __builtin_amdgcn_global_load_lds((const unsigned*)((const char*)(gbase) + (voff)[_i]), (LAS unsigned*)(lds + (bufoff) + ldsw + _i * 8192), 16, 0, 0); } while (0)
; #define PG8_LDA(dst, b, h) do { _Pragma("unroll") for (int m = 0; m < 4; ++m) _Pragma("unroll") for (int k = 0; k < 2; ++k) dst[m][k] = *(const LAS bf16x8*)(lds + PG8_SA(b, h) + aoff + m * 2048 + k * 1024); } while (0)
; #define PG8_LDB(dst, b, h) do { _Pragma("unroll") for (int n = 0; n < 2; ++n) _Pragma("unroll") for (int k = 0; k < 2; ++k) dst[n][k] = *(const LAS bf16x8*)(lds + PG8_SB(b, h) + boff + n * 2048 + k * 1024); } while (0)
; #define PG8_WAIT_V(n) asm volatile("s_waitcnt vmcnt(" #n ")" ::: "memory")
; #define PG8_WAIT_L(n) asm volatile("s_waitcnt lgkmcnt(" #n ")" ::: "memory")
; #define PG8_BAR __builtin_amdgcn_s_barrier()
; #define PG8_SCHED __builtin_amdgcn_sched_barrier(0)
; template <class Epi, class Sched, bool FUSED = false, bool APERM = false>
; __device__ __forceinline__ void gemm_phase(int wid_s, LAS unsigned char* lds, const Gemm g, const Sched& S, const Epi& E) {
;     ...
;             const bool last = (t == nt - 2);
;             const char* a1 = cA + (size_t)(t + 1) * kstep;
;             const char* a2 = last ? nA : cA + (size_t)(t + 2) * kstep; const char* b2 = last ? nB : cB + (size_t)(t + 2) * kstep;
;             const char* a3 = a2 + kstep; const char* b3 = b2 + kstep;
;             if (last && has_next) S.a_ready(nxt);
;             PG8_LDB(B0, 0, 0); PG8_LDB(B1, 0, 1); PG8_SCHED; PG8_LDA(At, 0, 0); PG8_STAGE(PG8_SA(1, 1), a1 + hstep, voffA);
;             PG8_WAIT_V(8); PG8_WAIT_L(0); PG8_BAR; PG8_MMA(0, 0, At, B0); PG8_MMA(0, 1, At, B1); PG8_BAR; PG8_SCHED;
;             PG8_LDA(At, 0, 1); PG8_STAGE(PG8_SB(0, 0), b2, voffB); PG8_STAGE(PG8_SB(0, 1), b2 + hstep, voffB); PG8_STAGE(PG8_SA(0, 0), a2, voffA);
;             PG8_WAIT_V(8); PG8_WAIT_L(0); PG8_BAR; PG8_MMA(1, 0, At, B0); PG8_MMA(1, 1, At, B1); PG8_BAR; PG8_SCHED;
.LBB0_754:
	s_add_u32 s36, s6, 0x100
	s_addc_u32 s37, s7, 0
	s_add_i32 s45, 0, 0x10000
	s_cmp_eq_u32 s44, 28
	s_cselect_b32 s41, s3, s37
	s_cselect_b32 s40, s5, s36
	s_cselect_b32 s39, s27, s43
	s_cselect_b32 s38, s29, s42
	s_add_i32 s63, 0, 0x14000
	v_add_u32_e32 v80, s45, v244
	v_add_u32_e32 v96, s63, v244
	ds_read_b128 v[68:71], v80
	ds_read_b128 v[72:75], v80 offset:1024
	ds_read_b128 v[76:79], v80 offset:2048
	ds_read_b128 v[80:83], v80 offset:3072
	ds_read_b128 v[84:87], v96
	ds_read_b128 v[88:91], v96 offset:1024
	ds_read_b128 v[92:95], v96 offset:2048
	ds_read_b128 v[96:99], v96 offset:3072
	v_lshl_add_u64 v[200:201], s[6:7], 0, v[216:217]
	s_add_i32 m0, s52, 0xc000
	ds_read_b128 v[164:167], v245
	ds_read_b128 v[168:171], v245 offset:1024
	ds_read_b128 v[172:175], v245 offset:2048
	ds_read_b128 v[176:179], v245 offset:3072
	ds_read_b128 v[180:183], v245 offset:4096
	ds_read_b128 v[184:187], v245 offset:5120
	ds_read_b128 v[188:191], v245 offset:6144
	ds_read_b128 v[192:195], v245 offset:7168
	global_load_lds_dwordx4 v[200:201], off
	v_lshl_add_u64 v[200:201], s[6:7], 0, v[214:215]
	s_add_i32 m0, s52, 0xe000
	s_nop 0
	global_load_lds_dwordx4 v[200:201], off
	s_waitcnt vmcnt(8)
	s_waitcnt lgkmcnt(0)
	s_barrier
	v_mfma_f32_16x16x32_f16 v[160:163], v[68:71], v[164:167], v[160:163]
	v_mfma_f32_16x16x32_f16 v[64:67], v[76:79], v[164:167], v[64:67]
	v_mfma_f32_16x16x32_f16 v[148:151], v[68:71], v[172:175], v[148:151]
	v_mfma_f32_16x16x32_f16 v[48:51], v[76:79], v[172:175], v[48:51]
	v_mfma_f32_16x16x32_f16 v[132:135], v[68:71], v[180:183], v[132:135]
	v_mfma_f32_16x16x32_f16 v[36:39], v[76:79], v[180:183], v[36:39]
	v_mfma_f32_16x16x32_f16 v[144:147], v[68:71], v[188:191], v[144:147]
	v_mfma_f32_16x16x32_f16 v[44:47], v[76:79], v[188:191], v[44:47]
	v_mfma_f32_16x16x32_f16 v[160:163], v[72:75], v[168:171], v[160:163]
	v_mfma_f32_16x16x32_f16 v[64:67], v[80:83], v[168:171], v[64:67]
	v_mfma_f32_16x16x32_f16 v[148:151], v[72:75], v[176:179], v[148:151]
	v_mfma_f32_16x16x32_f16 v[48:51], v[80:83], v[176:179], v[48:51]
	v_mfma_f32_16x16x32_f16 v[132:135], v[72:75], v[184:187], v[132:135]
	v_mfma_f32_16x16x32_f16 v[36:39], v[80:83], v[184:187], v[36:39]
	v_mfma_f32_16x16x32_f16 v[144:147], v[72:75], v[192:195], v[144:147]
	v_mfma_f32_16x16x32_f16 v[44:47], v[80:83], v[192:195], v[44:47]
	v_mfma_f32_16x16x32_f16 v[156:159], v[84:87], v[164:167], v[156:159]
	v_mfma_f32_16x16x32_f16 v[60:63], v[92:95], v[164:167], v[60:63]
	v_mfma_f32_16x16x32_f16 v[152:155], v[84:87], v[172:175], v[152:155]
	v_mfma_f32_16x16x32_f16 v[56:59], v[92:95], v[172:175], v[56:59]
	v_mfma_f32_16x16x32_f16 v[140:143], v[84:87], v[180:183], v[140:143]
	v_mfma_f32_16x16x32_f16 v[40:43], v[92:95], v[180:183], v[40:43]
	v_mfma_f32_16x16x32_f16 v[136:139], v[84:87], v[188:191], v[136:139]
	v_mfma_f32_16x16x32_f16 v[52:55], v[92:95], v[188:191], v[52:55]
	v_mfma_f32_16x16x32_f16 v[156:159], v[88:91], v[168:171], v[156:159]
	v_mfma_f32_16x16x32_f16 v[60:63], v[96:99], v[168:171], v[60:63]
	v_mfma_f32_16x16x32_f16 v[152:155], v[88:91], v[176:179], v[152:155]
	v_mfma_f32_16x16x32_f16 v[56:59], v[96:99], v[176:179], v[56:59]
	v_mfma_f32_16x16x32_f16 v[140:143], v[88:91], v[184:187], v[140:143]
	v_mfma_f32_16x16x32_f16 v[40:43], v[96:99], v[184:187], v[40:43]
	v_mfma_f32_16x16x32_f16 v[136:139], v[88:91], v[192:195], v[136:139]
	v_mfma_f32_16x16x32_f16 v[52:55], v[96:99], v[192:195], v[52:55]
	s_barrier
	s_add_i32 s6, s45, s51
	v_lshl_add_u64 v[200:201], s[38:39], 0, v[208:209]
	s_mov_b32 m0, s6
	ds_read_b128 v[164:167], v245 offset:16384
	ds_read_b128 v[168:171], v245 offset:17408
	ds_read_b128 v[172:175], v245 offset:18432
	ds_read_b128 v[176:179], v245 offset:19456
	ds_read_b128 v[180:183], v245 offset:20480
	ds_read_b128 v[184:187], v245 offset:21504
	ds_read_b128 v[188:191], v245 offset:22528
	ds_read_b128 v[192:195], v245 offset:23552
	global_load_lds_dwordx4 v[200:201], off
	s_add_i32 m0, s6, 0x2000
	s_add_u32 s6, s38, 0x80000
	v_lshl_add_u64 v[234:235], s[38:39], 0, v[212:213]
	s_addc_u32 s7, s39, 0
	s_add_i32 s45, s63, s51
	global_load_lds_dwordx4 v[234:235], off
	v_lshl_add_u64 v[218:219], s[6:7], 0, v[208:209]
	s_mov_b32 m0, s45
	v_lshl_add_u64 v[236:237], s[40:41], 0, v[0:1]
	global_load_lds_dwordx4 v[218:219], off
	v_lshl_add_u64 v[218:219], s[6:7], 0, v[212:213]
	s_add_i32 m0, s45, 0x2000
	v_lshl_add_u64 v[238:239], s[40:41], 0, v[210:211]
	global_load_lds_dwordx4 v[218:219], off
	s_mov_b32 m0, s52
	s_nop 0
	global_load_lds_dwordx4 v[236:237], off
	s_mov_b32 m0, s53
	s_nop 0
	global_load_lds_dwordx4 v[238:239], off
	s_waitcnt vmcnt(8)
	s_waitcnt lgkmcnt(0)
	s_barrier
; #define PG8_STAGE(bufoff, gbase, voff) do { _Pragma("unroll") for (int _i = 0; _i < 2; ++_i) \
;         __builtin_amdgcn_global_load_lds((const unsigned*)((const char*)(gbase) + (voff)[_i]), (LAS unsigned*)(lds + (bufoff) + ldsw + _i * 8192), 16, 0, 0); } while (0)
; #define PG8_LDA(dst, b, h) do { _Pragma("unroll") for (int m = 0; m < 4; ++m) _Pragma("unroll") for (int k = 0; k < 2; ++k) dst[m][k] = *(const LAS bf16x8*)(lds + PG8_SA(b, h) + aoff + m * 2048 + k * 1024); } while (0)
; #define PG8_LDB(dst, b, h) do { _Pragma("unroll") for (int n = 0; n < 2; ++n) _Pragma("unroll") for (int k = 0; k < 2; ++k) dst[n][k] = *(const LAS bf16x8*)(lds + PG8_SB(b, h) + boff + n * 2048 + k * 1024); } while (0)
; #define PG8_WAIT_V(n) asm volatile("s_waitcnt vmcnt(" #n ")" ::: "memory")
; #define PG8_WAIT_L(n) asm volatile("s_waitcnt lgkmcnt(" #n ")" ::: "memory")
; #define PG8_BAR __builtin_amdgcn_s_barrier()
; #define PG8_SCHED __builtin_amdgcn_sched_barrier(0)
; template <class Epi, class Sched, bool FUSED = false, bool APERM = false>
; __device__ __forceinline__ void gemm_phase(int wid_s, LAS unsigned char* lds, const Gemm g, const Sched& S, const Epi& E) {
;     ...
;             PG8_WAIT_V(8); PG8_WAIT_L(0); PG8_BAR; PG8_MMA(1, 0, At, B0); PG8_MMA(1, 1, At, B1); PG8_BAR; PG8_SCHED;
;             PG8_LDB(B0, 1, 0); PG8_LDB(B1, 1, 1); PG8_SCHED; PG8_LDA(At, 1, 0); PG8_STAGE(PG8_SA(0, 1), a2 + hstep, voffA);
;             PG8_WAIT_V(8); PG8_WAIT_L(0); PG8_BAR; PG8_MMA(0, 0, At, B0); PG8_MMA(0, 1, At, B1); PG8_BAR; PG8_SCHED;
	v_mfma_f32_16x16x32_f16 v[128:131], v[68:71], v[164:167], v[128:131]
	v_mfma_f32_16x16x32_f16 v[32:35], v[76:79], v[164:167], v[32:35]
	v_mfma_f32_16x16x32_f16 v[120:123], v[68:71], v[172:175], v[120:123]
	v_mfma_f32_16x16x32_f16 v[24:27], v[76:79], v[172:175], v[24:27]
	v_mfma_f32_16x16x32_f16 v[100:103], v[68:71], v[180:183], v[100:103]
	v_mfma_f32_16x16x32_f16 v[8:11], v[76:79], v[180:183], v[8:11]
	v_mfma_f32_16x16x32_f16 v[112:115], v[68:71], v[188:191], v[112:115]
	v_mfma_f32_16x16x32_f16 v[4:7], v[76:79], v[188:191], v[4:7]
	v_mfma_f32_16x16x32_f16 v[128:131], v[72:75], v[168:171], v[128:131]
	v_mfma_f32_16x16x32_f16 v[32:35], v[80:83], v[168:171], v[32:35]
	v_mfma_f32_16x16x32_f16 v[120:123], v[72:75], v[176:179], v[120:123]
	v_mfma_f32_16x16x32_f16 v[24:27], v[80:83], v[176:179], v[24:27]
	v_mfma_f32_16x16x32_f16 v[100:103], v[72:75], v[184:187], v[100:103]
	v_mfma_f32_16x16x32_f16 v[8:11], v[80:83], v[184:187], v[8:11]
	v_mfma_f32_16x16x32_f16 v[112:115], v[72:75], v[192:195], v[112:115]
	v_mfma_f32_16x16x32_f16 v[4:7], v[80:83], v[192:195], v[4:7]
	v_mfma_f32_16x16x32_f16 v[28:31], v[92:95], v[164:167], v[28:31]
	v_mfma_f32_16x16x32_f16 v[20:23], v[92:95], v[172:175], v[20:23]
	v_mfma_f32_16x16x32_f16 v[16:19], v[92:95], v[180:183], v[16:19]
	v_mfma_f32_16x16x32_f16 v[12:15], v[92:95], v[188:191], v[12:15]
	v_mfma_f32_16x16x32_f16 v[68:71], v[84:87], v[164:167], v[124:127]
	v_mfma_f32_16x16x32_f16 v[28:31], v[96:99], v[168:171], v[28:31]
	v_mfma_f32_16x16x32_f16 v[72:75], v[84:87], v[172:175], v[116:119]
	v_mfma_f32_16x16x32_f16 v[20:23], v[96:99], v[176:179], v[20:23]
	v_mfma_f32_16x16x32_f16 v[76:79], v[84:87], v[180:183], v[108:111]
	v_mfma_f32_16x16x32_f16 v[16:19], v[96:99], v[184:187], v[16:19]
	v_mfma_f32_16x16x32_f16 v[80:83], v[84:87], v[188:191], v[104:107]
	v_mfma_f32_16x16x32_f16 v[12:15], v[96:99], v[192:195], v[12:15]
	v_mfma_f32_16x16x32_f16 v[68:71], v[88:91], v[168:171], v[68:71]
	v_mfma_f32_16x16x32_f16 v[72:75], v[88:91], v[176:179], v[72:75]
	v_mfma_f32_16x16x32_f16 v[76:79], v[88:91], v[184:187], v[76:79]
	v_mfma_f32_16x16x32_f16 v[80:83], v[88:91], v[192:195], v[80:83]
	s_barrier
	s_add_i32 s45, 0, 0x18000
	s_add_i32 s63, 0, 0x1c000
	v_add_u32_e32 v96, s45, v244
	v_add_u32_e32 v104, s63, v244
	ds_read_b128 v[84:87], v96
	ds_read_b128 v[88:91], v96 offset:1024
	ds_read_b128 v[92:95], v96 offset:2048
	ds_read_b128 v[96:99], v96 offset:3072
	ds_read_b128 v[164:167], v104
	ds_read_b128 v[168:171], v104 offset:1024
	ds_read_b128 v[172:175], v104 offset:2048
	ds_read_b128 v[176:179], v104 offset:3072
	s_add_u32 s6, s40, 0x80000
	s_addc_u32 s7, s41, 0
	s_mov_b32 m0, s54
	v_lshl_add_u64 v[218:219], s[6:7], 0, v[0:1]
	ds_read_b128 v[104:107], v245 offset:32768
	ds_read_b128 v[108:111], v245 offset:33792
	ds_read_b128 v[116:119], v245 offset:34816
	ds_read_b128 v[124:127], v245 offset:35840
	ds_read_b128 v[180:183], v245 offset:36864
	ds_read_b128 v[184:187], v245 offset:37888
	ds_read_b128 v[188:191], v245 offset:38912
	ds_read_b128 v[192:195], v245 offset:39936
	global_load_lds_dwordx4 v[218:219], off
	v_lshl_add_u64 v[218:219], s[6:7], 0, v[210:211]
	s_mov_b32 m0, s55
	s_nop 0
	global_load_lds_dwordx4 v[218:219], off
	s_waitcnt vmcnt(8)
	s_waitcnt lgkmcnt(0)
	s_barrier
	v_mfma_f32_16x16x32_f16 v[160:163], v[84:87], v[104:107], v[160:163]
	v_mfma_f32_16x16x32_f16 v[64:67], v[92:95], v[104:107], v[64:67]
	v_mfma_f32_16x16x32_f16 v[148:151], v[84:87], v[116:119], v[148:151]
	v_mfma_f32_16x16x32_f16 v[48:51], v[92:95], v[116:119], v[48:51]
	v_mfma_f32_16x16x32_f16 v[132:135], v[84:87], v[180:183], v[132:135]
	v_mfma_f32_16x16x32_f16 v[36:39], v[92:95], v[180:183], v[36:39]
	v_mfma_f32_16x16x32_f16 v[144:147], v[84:87], v[188:191], v[144:147]
	v_mfma_f32_16x16x32_f16 v[44:47], v[92:95], v[188:191], v[44:47]
	v_mfma_f32_16x16x32_f16 v[160:163], v[88:91], v[108:111], v[160:163]
	v_mfma_f32_16x16x32_f16 v[64:67], v[96:99], v[108:111], v[64:67]
	v_mfma_f32_16x16x32_f16 v[148:151], v[88:91], v[124:127], v[148:151]
	v_mfma_f32_16x16x32_f16 v[48:51], v[96:99], v[124:127], v[48:51]
	v_mfma_f32_16x16x32_f16 v[132:135], v[88:91], v[184:187], v[132:135]
	v_mfma_f32_16x16x32_f16 v[36:39], v[96:99], v[184:187], v[36:39]
	v_mfma_f32_16x16x32_f16 v[144:147], v[88:91], v[192:195], v[144:147]
	v_mfma_f32_16x16x32_f16 v[44:47], v[96:99], v[192:195], v[44:47]
	v_mfma_f32_16x16x32_f16 v[156:159], v[164:167], v[104:107], v[156:159]
	v_mfma_f32_16x16x32_f16 v[60:63], v[172:175], v[104:107], v[60:63]
	v_mfma_f32_16x16x32_f16 v[152:155], v[164:167], v[116:119], v[152:155]
	v_mfma_f32_16x16x32_f16 v[56:59], v[172:175], v[116:119], v[56:59]
	v_mfma_f32_16x16x32_f16 v[140:143], v[164:167], v[180:183], v[140:143]
	v_mfma_f32_16x16x32_f16 v[40:43], v[172:175], v[180:183], v[40:43]
	v_mfma_f32_16x16x32_f16 v[136:139], v[164:167], v[188:191], v[136:139]
	v_mfma_f32_16x16x32_f16 v[52:55], v[172:175], v[188:191], v[52:55]
	v_mfma_f32_16x16x32_f16 v[156:159], v[168:171], v[108:111], v[156:159]
	v_mfma_f32_16x16x32_f16 v[60:63], v[176:179], v[108:111], v[60:63]
	v_mfma_f32_16x16x32_f16 v[152:155], v[168:171], v[124:127], v[152:155]
	v_mfma_f32_16x16x32_f16 v[56:59], v[176:179], v[124:127], v[56:59]
	v_mfma_f32_16x16x32_f16 v[140:143], v[168:171], v[184:187], v[140:143]
	v_mfma_f32_16x16x32_f16 v[40:43], v[176:179], v[184:187], v[40:43]
	v_mfma_f32_16x16x32_f16 v[136:139], v[168:171], v[192:195], v[136:139]
	v_mfma_f32_16x16x32_f16 v[52:55], v[176:179], v[192:195], v[52:55]
	s_barrier
; #define PG8_STAGE(bufoff, gbase, voff) do { _Pragma("unroll") for (int _i = 0; _i < 2; ++_i) \
;         __builtin_amdgcn_global_load_lds((const unsigned*)((const char*)(gbase) + (voff)[_i]), (LAS unsigned*)(lds + (bufoff) + ldsw + _i * 8192), 16, 0, 0); } while (0)
; #define PG8_LDA(dst, b, h) do { _Pragma("unroll") for (int m = 0; m < 4; ++m) _Pragma("unroll") for (int k = 0; k < 2; ++k) dst[m][k] = *(const LAS bf16x8*)(lds + PG8_SA(b, h) + aoff + m * 2048 + k * 1024); } while (0)
; #define PG8_WAIT_V(n) asm volatile("s_waitcnt vmcnt(" #n ")" ::: "memory")
; #define PG8_WAIT_L(n) asm volatile("s_waitcnt lgkmcnt(" #n ")" ::: "memory")
; #define PG8_BAR __builtin_amdgcn_s_barrier()
; #define PG8_SCHED __builtin_amdgcn_sched_barrier(0)
; template <class Epi, class Sched, bool FUSED = false, bool APERM = false>
; __device__ __forceinline__ void gemm_phase(int wid_s, LAS unsigned char* lds, const Gemm g, const Sched& S, const Epi& E) {
;     ...
;             PG8_LDA(At, 1, 1); PG8_STAGE(PG8_SB(1, 0), b3, voffB); PG8_STAGE(PG8_SB(1, 1), b3 + hstep, voffB); PG8_STAGE(PG8_SA(1, 0), a3, voffA);
;             PG8_WAIT_V(8); PG8_WAIT_L(0); PG8_BAR; PG8_MMA(1, 0, At, B0); PG8_MMA(1, 1, At, B1); PG8_BAR; PG8_SCHED;
;         }
;         if (wr == 0) PG8_BAR;
	s_add_i32 s6, s45, s51
	v_lshl_add_u64 v[104:105], v[200:201], 0, s[12:13]
	s_mov_b32 m0, s6
	ds_read_b128 v[180:183], v245 offset:49152
	ds_read_b128 v[184:187], v245 offset:50176
	ds_read_b128 v[188:191], v245 offset:51200
	ds_read_b128 v[192:195], v245 offset:52224
	ds_read_b128 v[218:221], v245 offset:53248
	ds_read_b128 v[222:225], v245 offset:54272
	ds_read_b128 v[226:229], v245 offset:55296
	ds_read_b128 v[230:233], v245 offset:56320
	global_load_lds_dwordx4 v[104:105], off
	s_add_i32 m0, s6, 0x2000
	s_add_u32 s6, s38, 0x80080
	v_lshl_add_u64 v[104:105], v[234:235], 0, s[12:13]
	s_addc_u32 s7, s39, 0
	s_add_i32 s38, s63, s51
	global_load_lds_dwordx4 v[104:105], off
	v_lshl_add_u64 v[104:105], s[6:7], 0, v[208:209]
	s_mov_b32 m0, s38
	s_nop 0
	global_load_lds_dwordx4 v[104:105], off
	v_lshl_add_u64 v[104:105], s[6:7], 0, v[212:213]
	s_add_i32 m0, s38, 0x2000
	s_nop 0
	global_load_lds_dwordx4 v[104:105], off
	v_lshl_add_u64 v[104:105], v[236:237], 0, s[12:13]
	s_mov_b32 m0, s59
	s_nop 0
	global_load_lds_dwordx4 v[104:105], off
	v_lshl_add_u64 v[104:105], v[238:239], 0, s[12:13]
	s_mov_b32 m0, s60
	s_nop 0
	global_load_lds_dwordx4 v[104:105], off
	s_waitcnt vmcnt(8)
	s_waitcnt lgkmcnt(0)
	s_barrier
	v_mfma_f32_16x16x32_f16 v[104:107], v[84:87], v[180:183], v[128:131]
	v_mfma_f32_16x16x32_f16 v[128:131], v[88:91], v[184:187], v[104:107]
	v_mfma_f32_16x16x32_f16 v[104:107], v[84:87], v[188:191], v[120:123]
	v_mfma_f32_16x16x32_f16 v[32:35], v[92:95], v[180:183], v[32:35]
	v_mfma_f32_16x16x32_f16 v[120:123], v[88:91], v[192:195], v[104:107]
	v_mfma_f32_16x16x32_f16 v[24:27], v[92:95], v[188:191], v[24:27]
	v_mfma_f32_16x16x32_f16 v[100:103], v[84:87], v[218:221], v[100:103]
	v_mfma_f32_16x16x32_f16 v[8:11], v[92:95], v[218:221], v[8:11]
	v_mfma_f32_16x16x32_f16 v[104:107], v[84:87], v[226:229], v[112:115]
	v_mfma_f32_16x16x32_f16 v[4:7], v[92:95], v[226:229], v[4:7]
	v_mfma_f32_16x16x32_f16 v[32:35], v[96:99], v[184:187], v[32:35]
	v_mfma_f32_16x16x32_f16 v[24:27], v[96:99], v[192:195], v[24:27]
	v_mfma_f32_16x16x32_f16 v[100:103], v[88:91], v[222:225], v[100:103]
	v_mfma_f32_16x16x32_f16 v[8:11], v[96:99], v[222:225], v[8:11]
	v_mfma_f32_16x16x32_f16 v[112:115], v[88:91], v[230:233], v[104:107]
	v_mfma_f32_16x16x32_f16 v[4:7], v[96:99], v[230:233], v[4:7]
	v_mfma_f32_16x16x32_f16 v[68:71], v[164:167], v[180:183], v[68:71]
	v_mfma_f32_16x16x32_f16 v[124:127], v[168:171], v[184:187], v[68:71]
	v_mfma_f32_16x16x32_f16 v[68:71], v[164:167], v[188:191], v[72:75]
	v_mfma_f32_16x16x32_f16 v[116:119], v[168:171], v[192:195], v[68:71]
	v_mfma_f32_16x16x32_f16 v[68:71], v[164:167], v[218:221], v[76:79]
	v_mfma_f32_16x16x32_f16 v[28:31], v[172:175], v[180:183], v[28:31]
	v_mfma_f32_16x16x32_f16 v[20:23], v[172:175], v[188:191], v[20:23]
	v_mfma_f32_16x16x32_f16 v[108:111], v[168:171], v[222:225], v[68:71]
	v_mfma_f32_16x16x32_f16 v[16:19], v[172:175], v[218:221], v[16:19]
	v_mfma_f32_16x16x32_f16 v[68:71], v[164:167], v[226:229], v[80:83]
	v_mfma_f32_16x16x32_f16 v[12:15], v[172:175], v[226:229], v[12:15]
	v_mfma_f32_16x16x32_f16 v[28:31], v[176:179], v[184:187], v[28:31]
	v_mfma_f32_16x16x32_f16 v[20:23], v[176:179], v[192:195], v[20:23]
	v_mfma_f32_16x16x32_f16 v[16:19], v[176:179], v[222:225], v[16:19]
	v_mfma_f32_16x16x32_f16 v[104:107], v[168:171], v[230:233], v[68:71]
	v_mfma_f32_16x16x32_f16 v[12:15], v[176:179], v[230:233], v[12:15]
	s_barrier
	s_add_i32 s44, s44, 2
	s_add_u32 s42, s42, 0x100
	s_addc_u32 s43, s43, 0
	s_cmp_gt_u32 s44, 29
	s_mov_b64 s[6:7], s[36:37]
	s_cbranch_scc0 .LBB0_754
	s_and_b64 vcc, exec, s[24:25]
	s_cbranch_vccz .LBB0_757
	s_barrier

; #define PG8_STAGE(bufoff, gbase, voff) do { _Pragma("unroll") for (int _i = 0; _i < 2; ++_i) \
;         __builtin_amdgcn_global_load_lds((const unsigned*)((const char*)(gbase) + (voff)[_i]), (LAS unsigned*)(lds + (bufoff) + ldsw + _i * 8192), 16, 0, 0); } while (0)
; #define PG8_LDA(dst, b, h) do { _Pragma("unroll") for (int m = 0; m < 4; ++m) _Pragma("unroll") for (int k = 0; k < 2; ++k) dst[m][k] = *(const LAS bf16x8*)(lds + PG8_SA(b, h) + aoff + m * 2048 + k * 1024); } while (0)
; #define PG8_LDB(dst, b, h) do { _Pragma("unroll") for (int n = 0; n < 2; ++n) _Pragma("unroll") for (int k = 0; k < 2; ++k) dst[n][k] = *(const LAS bf16x8*)(lds + PG8_SB(b, h) + boff + n * 2048 + k * 1024); } while (0)
; #define PG8_WAIT_V(n) asm volatile("s_waitcnt vmcnt(" #n ")" ::: "memory")
; #define PG8_WAIT_L(n) asm volatile("s_waitcnt lgkmcnt(" #n ")" ::: "memory")
; #define PG8_BAR __builtin_amdgcn_s_barrier()
; #define PG8_SCHED __builtin_amdgcn_sched_barrier(0)
; template <class Epi, class Sched, bool FUSED = false, bool APERM = false>
; __device__ __forceinline__ void gemm_phase(int wid_s, LAS unsigned char* lds, const Gemm g, const Sched& S, const Epi& E) {
;     ...
;             const bool last = (t == nt - 2);
;             const char* a1 = cA + (size_t)(t + 1) * kstep;
;             const char* a2 = last ? nA : cA + (size_t)(t + 2) * kstep; const char* b2 = last ? nB : cB + (size_t)(t + 2) * kstep;
;             const char* a3 = a2 + kstep; const char* b3 = b2 + kstep;
;             if (last && has_next) S.a_ready(nxt);
;             PG8_LDB(B0, 0, 0); PG8_LDB(B1, 0, 1); PG8_SCHED; PG8_LDA(At, 0, 0); PG8_STAGE(PG8_SA(1, 1), a1 + hstep, voffA);
;             PG8_WAIT_V(8); PG8_WAIT_L(0); PG8_BAR; PG8_MMA(0, 0, At, B0); PG8_MMA(0, 1, At, B1); PG8_BAR; PG8_SCHED;
;             PG8_LDA(At, 0, 1); PG8_STAGE(PG8_SB(0, 0), b2, voffB); PG8_STAGE(PG8_SB(0, 1), b2 + hstep, voffB); PG8_STAGE(PG8_SA(0, 0), a2, voffA);
;             PG8_WAIT_V(8); PG8_WAIT_L(0); PG8_BAR; PG8_MMA(1, 0, At, B0); PG8_MMA(1, 1, At, B1); PG8_BAR; PG8_SCHED;
.LBB0_929:
	s_add_u32 s36, s28, s34
	s_addc_u32 s37, s29, s35
	s_add_u32 s36, s36, 0x100
	s_addc_u32 s37, s37, 0
	s_add_u32 s63, s60, s34
	s_addc_u32 s64, s61, s35
	s_add_i32 s65, 0, 0x10000
	s_cmpk_eq_i32 s34, 0x2a00
	s_cselect_b32 s39, s5, s37
	s_cselect_b32 s38, s4, s36
	v_add_u32_e32 v143, s65, v3
	s_cselect_b32 s37, s31, s64
	s_cselect_b32 s36, s30, s63
	s_add_i32 s63, 0, 0x14000
	ds_read_b128 v[144:147], v143
	ds_read_b128 v[148:151], v143 offset:1024
	ds_read_b128 v[152:155], v143 offset:2048
	ds_read_b128 v[156:159], v143 offset:3072
	v_add_u32_e32 v143, s63, v3
	ds_read_b128 v[160:163], v143
	ds_read_b128 v[164:167], v143 offset:1024
	ds_read_b128 v[168:171], v143 offset:2048
	ds_read_b128 v[172:175], v143 offset:3072
	v_lshl_add_u64 v[200:201], v[140:141], 0, s[34:35]
	s_add_i32 m0, s49, 0xc000
	ds_read_b128 v[176:179], v142
	ds_read_b128 v[180:183], v142 offset:1024
	ds_read_b128 v[184:187], v142 offset:2048
	ds_read_b128 v[188:191], v142 offset:3072
	ds_read_b128 v[192:195], v142 offset:4096
	ds_read_b128 v[208:211], v142 offset:5120
	ds_read_b128 v[212:215], v142 offset:6144
	ds_read_b128 v[216:219], v142 offset:7168
	global_load_lds_dwordx4 v[200:201], off
	v_lshl_add_u64 v[200:201], v[138:139], 0, s[34:35]
	s_add_i32 m0, s49, 0xe000
	s_nop 0
	global_load_lds_dwordx4 v[200:201], off
	s_waitcnt vmcnt(8)
	s_waitcnt lgkmcnt(0)
	s_barrier
	v_mfma_f32_16x16x32_f16 v[128:131], v[144:147], v[176:179], v[128:131]
	v_mfma_f32_16x16x32_f16 v[124:127], v[152:155], v[176:179], v[124:127]
	v_mfma_f32_16x16x32_f16 v[112:115], v[144:147], v[184:187], v[112:115]
	v_mfma_f32_16x16x32_f16 v[108:111], v[152:155], v[184:187], v[108:111]
	v_mfma_f32_16x16x32_f16 v[96:99], v[144:147], v[192:195], v[96:99]
	v_mfma_f32_16x16x32_f16 v[92:95], v[152:155], v[192:195], v[92:95]
	v_mfma_f32_16x16x32_f16 v[80:83], v[144:147], v[212:215], v[80:83]
	v_mfma_f32_16x16x32_f16 v[76:79], v[152:155], v[212:215], v[76:79]
	v_mfma_f32_16x16x32_f16 v[128:131], v[148:151], v[180:183], v[128:131]
	v_mfma_f32_16x16x32_f16 v[124:127], v[156:159], v[180:183], v[124:127]
	v_mfma_f32_16x16x32_f16 v[112:115], v[148:151], v[188:191], v[112:115]
	v_mfma_f32_16x16x32_f16 v[108:111], v[156:159], v[188:191], v[108:111]
	v_mfma_f32_16x16x32_f16 v[96:99], v[148:151], v[208:211], v[96:99]
	v_mfma_f32_16x16x32_f16 v[92:95], v[156:159], v[208:211], v[92:95]
	v_mfma_f32_16x16x32_f16 v[80:83], v[148:151], v[216:219], v[80:83]
	v_mfma_f32_16x16x32_f16 v[76:79], v[156:159], v[216:219], v[76:79]
	v_mfma_f32_16x16x32_f16 v[120:123], v[160:163], v[176:179], v[120:123]
	v_mfma_f32_16x16x32_f16 v[116:119], v[168:171], v[176:179], v[116:119]
	v_mfma_f32_16x16x32_f16 v[104:107], v[160:163], v[184:187], v[104:107]
	v_mfma_f32_16x16x32_f16 v[100:103], v[168:171], v[184:187], v[100:103]
	v_mfma_f32_16x16x32_f16 v[88:91], v[160:163], v[192:195], v[88:91]
	v_mfma_f32_16x16x32_f16 v[84:87], v[168:171], v[192:195], v[84:87]
	v_mfma_f32_16x16x32_f16 v[72:75], v[160:163], v[212:215], v[72:75]
	v_mfma_f32_16x16x32_f16 v[68:71], v[168:171], v[212:215], v[68:71]
	v_mfma_f32_16x16x32_f16 v[120:123], v[164:167], v[180:183], v[120:123]
	v_mfma_f32_16x16x32_f16 v[116:119], v[172:175], v[180:183], v[116:119]
	v_mfma_f32_16x16x32_f16 v[104:107], v[164:167], v[188:191], v[104:107]
	v_mfma_f32_16x16x32_f16 v[100:103], v[172:175], v[188:191], v[100:103]
	v_mfma_f32_16x16x32_f16 v[88:91], v[164:167], v[208:211], v[88:91]
	v_mfma_f32_16x16x32_f16 v[84:87], v[172:175], v[208:211], v[84:87]
	v_mfma_f32_16x16x32_f16 v[72:75], v[164:167], v[216:219], v[72:75]
	v_mfma_f32_16x16x32_f16 v[68:71], v[172:175], v[216:219], v[68:71]
	s_barrier
	s_add_i32 s64, s65, s48
	v_lshl_add_u64 v[200:201], s[36:37], 0, v[0:1]
	s_mov_b32 m0, s64
	ds_read_b128 v[176:179], v142 offset:16384
	ds_read_b128 v[180:183], v142 offset:17408
	ds_read_b128 v[184:187], v142 offset:18432
	ds_read_b128 v[188:191], v142 offset:19456
	ds_read_b128 v[192:195], v142 offset:20480
	ds_read_b128 v[208:211], v142 offset:21504
	ds_read_b128 v[212:215], v142 offset:22528
	ds_read_b128 v[216:219], v142 offset:23552
	global_load_lds_dwordx4 v[200:201], off
	s_add_i32 m0, s64, 0x2000
	s_add_u32 s64, s36, 0x158000
	v_lshl_add_u64 v[222:223], s[36:37], 0, v[132:133]
	s_addc_u32 s65, s37, 0
	s_add_i32 s63, s63, s48
	global_load_lds_dwordx4 v[222:223], off
	v_lshl_add_u64 v[224:225], s[64:65], 0, v[0:1]
	s_mov_b32 m0, s63
	v_lshl_add_u64 v[226:227], s[38:39], 0, v[132:133]
	global_load_lds_dwordx4 v[224:225], off
	v_lshl_add_u64 v[224:225], s[64:65], 0, v[132:133]
	s_add_i32 m0, s63, 0x2000
	s_nop 0
	global_load_lds_dwordx4 v[224:225], off
	v_lshl_add_u64 v[224:225], s[38:39], 0, v[0:1]
	s_mov_b32 m0, s49
	s_nop 0
	global_load_lds_dwordx4 v[224:225], off
	s_mov_b32 m0, s50
	s_nop 0
	global_load_lds_dwordx4 v[226:227], off
	s_waitcnt vmcnt(8)
	s_waitcnt lgkmcnt(0)
	s_barrier
; #define PG8_STAGE(bufoff, gbase, voff) do { _Pragma("unroll") for (int _i = 0; _i < 2; ++_i) \
;         __builtin_amdgcn_global_load_lds((const unsigned*)((const char*)(gbase) + (voff)[_i]), (LAS unsigned*)(lds + (bufoff) + ldsw + _i * 8192), 16, 0, 0); } while (0)
; #define PG8_LDA(dst, b, h) do { _Pragma("unroll") for (int m = 0; m < 4; ++m) _Pragma("unroll") for (int k = 0; k < 2; ++k) dst[m][k] = *(const LAS bf16x8*)(lds + PG8_SA(b, h) + aoff + m * 2048 + k * 1024); } while (0)
; #define PG8_LDB(dst, b, h) do { _Pragma("unroll") for (int n = 0; n < 2; ++n) _Pragma("unroll") for (int k = 0; k < 2; ++k) dst[n][k] = *(const LAS bf16x8*)(lds + PG8_SB(b, h) + boff + n * 2048 + k * 1024); } while (0)
; #define PG8_WAIT_V(n) asm volatile("s_waitcnt vmcnt(" #n ")" ::: "memory")
; #define PG8_WAIT_L(n) asm volatile("s_waitcnt lgkmcnt(" #n ")" ::: "memory")
; #define PG8_BAR __builtin_amdgcn_s_barrier()
; #define PG8_SCHED __builtin_amdgcn_sched_barrier(0)
; template <class Epi, class Sched, bool FUSED = false, bool APERM = false>
; __device__ __forceinline__ void gemm_phase(int wid_s, LAS unsigned char* lds, const Gemm g, const Sched& S, const Epi& E) {
;     ...
;             PG8_WAIT_V(8); PG8_WAIT_L(0); PG8_BAR; PG8_MMA(1, 0, At, B0); PG8_MMA(1, 1, At, B1); PG8_BAR; PG8_SCHED;
;             PG8_LDB(B0, 1, 0); PG8_LDB(B1, 1, 1); PG8_SCHED; PG8_LDA(At, 1, 0); PG8_STAGE(PG8_SA(0, 1), a2 + hstep, voffA);
;             PG8_WAIT_V(8); PG8_WAIT_L(0); PG8_BAR; PG8_MMA(0, 0, At, B0); PG8_MMA(0, 1, At, B1); PG8_BAR; PG8_SCHED;
	v_mfma_f32_16x16x32_f16 v[64:67], v[144:147], v[176:179], v[64:67]
	v_mfma_f32_16x16x32_f16 v[60:63], v[152:155], v[176:179], v[60:63]
	v_mfma_f32_16x16x32_f16 v[48:51], v[144:147], v[184:187], v[48:51]
	v_mfma_f32_16x16x32_f16 v[44:47], v[152:155], v[184:187], v[44:47]
	v_mfma_f32_16x16x32_f16 v[32:35], v[144:147], v[192:195], v[32:35]
	v_mfma_f32_16x16x32_f16 v[28:31], v[152:155], v[192:195], v[28:31]
	v_mfma_f32_16x16x32_f16 v[16:19], v[144:147], v[212:215], v[16:19]
	v_mfma_f32_16x16x32_f16 v[12:15], v[152:155], v[212:215], v[12:15]
	v_mfma_f32_16x16x32_f16 v[64:67], v[148:151], v[180:183], v[64:67]
	v_mfma_f32_16x16x32_f16 v[60:63], v[156:159], v[180:183], v[60:63]
	v_mfma_f32_16x16x32_f16 v[48:51], v[148:151], v[188:191], v[48:51]
	v_mfma_f32_16x16x32_f16 v[44:47], v[156:159], v[188:191], v[44:47]
	v_mfma_f32_16x16x32_f16 v[32:35], v[148:151], v[208:211], v[32:35]
	v_mfma_f32_16x16x32_f16 v[28:31], v[156:159], v[208:211], v[28:31]
	v_mfma_f32_16x16x32_f16 v[16:19], v[148:151], v[216:219], v[16:19]
	v_mfma_f32_16x16x32_f16 v[12:15], v[156:159], v[216:219], v[12:15]
	v_mfma_f32_16x16x32_f16 v[56:59], v[160:163], v[176:179], v[56:59]
	v_mfma_f32_16x16x32_f16 v[52:55], v[168:171], v[176:179], v[52:55]
	v_mfma_f32_16x16x32_f16 v[40:43], v[160:163], v[184:187], v[40:43]
	v_mfma_f32_16x16x32_f16 v[36:39], v[168:171], v[184:187], v[36:39]
	v_mfma_f32_16x16x32_f16 v[24:27], v[160:163], v[192:195], v[24:27]
	v_mfma_f32_16x16x32_f16 v[20:23], v[168:171], v[192:195], v[20:23]
	v_mfma_f32_16x16x32_f16 v[8:11], v[160:163], v[212:215], v[8:11]
	v_mfma_f32_16x16x32_f16 v[4:7], v[168:171], v[212:215], v[4:7]
	v_mfma_f32_16x16x32_f16 v[56:59], v[164:167], v[180:183], v[56:59]
	v_mfma_f32_16x16x32_f16 v[52:55], v[172:175], v[180:183], v[52:55]
	v_mfma_f32_16x16x32_f16 v[40:43], v[164:167], v[188:191], v[40:43]
	v_mfma_f32_16x16x32_f16 v[36:39], v[172:175], v[188:191], v[36:39]
	v_mfma_f32_16x16x32_f16 v[24:27], v[164:167], v[208:211], v[24:27]
	v_mfma_f32_16x16x32_f16 v[20:23], v[172:175], v[208:211], v[20:23]
	v_mfma_f32_16x16x32_f16 v[8:11], v[164:167], v[216:219], v[8:11]
	v_mfma_f32_16x16x32_f16 v[4:7], v[172:175], v[216:219], v[4:7]
	s_barrier
	s_add_i32 s63, 0, 0x18000
	v_add_u32_e32 v143, s63, v3
	s_add_i32 s64, 0, 0x1c000
	ds_read_b128 v[144:147], v143
	ds_read_b128 v[148:151], v143 offset:1024
	ds_read_b128 v[152:155], v143 offset:2048
	ds_read_b128 v[156:159], v143 offset:3072
	v_add_u32_e32 v143, s64, v3
	ds_read_b128 v[160:163], v143
	ds_read_b128 v[164:167], v143 offset:1024
	ds_read_b128 v[168:171], v143 offset:2048
	ds_read_b128 v[172:175], v143 offset:3072
	s_add_u32 s38, s38, 0x158000
	s_addc_u32 s39, s39, 0
	s_mov_b32 m0, s51
	v_lshl_add_u64 v[228:229], s[38:39], 0, v[0:1]
	ds_read_b128 v[176:179], v142 offset:32768
	ds_read_b128 v[180:183], v142 offset:33792
	ds_read_b128 v[184:187], v142 offset:34816
	ds_read_b128 v[188:191], v142 offset:35840
	ds_read_b128 v[192:195], v142 offset:36864
	ds_read_b128 v[208:211], v142 offset:37888
	ds_read_b128 v[212:215], v142 offset:38912
	ds_read_b128 v[216:219], v142 offset:39936
	global_load_lds_dwordx4 v[228:229], off
	v_lshl_add_u64 v[228:229], s[38:39], 0, v[132:133]
	s_mov_b32 m0, s52
	s_nop 0
	global_load_lds_dwordx4 v[228:229], off
	s_waitcnt vmcnt(8)
	s_waitcnt lgkmcnt(0)
	s_barrier
	v_mfma_f32_16x16x32_f16 v[128:131], v[144:147], v[176:179], v[128:131]
	v_mfma_f32_16x16x32_f16 v[124:127], v[152:155], v[176:179], v[124:127]
	v_mfma_f32_16x16x32_f16 v[112:115], v[144:147], v[184:187], v[112:115]
	v_mfma_f32_16x16x32_f16 v[108:111], v[152:155], v[184:187], v[108:111]
	v_mfma_f32_16x16x32_f16 v[96:99], v[144:147], v[192:195], v[96:99]
	v_mfma_f32_16x16x32_f16 v[92:95], v[152:155], v[192:195], v[92:95]
	v_mfma_f32_16x16x32_f16 v[80:83], v[144:147], v[212:215], v[80:83]
	v_mfma_f32_16x16x32_f16 v[76:79], v[152:155], v[212:215], v[76:79]
	v_mfma_f32_16x16x32_f16 v[128:131], v[148:151], v[180:183], v[128:131]
	v_mfma_f32_16x16x32_f16 v[124:127], v[156:159], v[180:183], v[124:127]
	v_mfma_f32_16x16x32_f16 v[112:115], v[148:151], v[188:191], v[112:115]
	v_mfma_f32_16x16x32_f16 v[108:111], v[156:159], v[188:191], v[108:111]
	v_mfma_f32_16x16x32_f16 v[96:99], v[148:151], v[208:211], v[96:99]
	v_mfma_f32_16x16x32_f16 v[92:95], v[156:159], v[208:211], v[92:95]
	v_mfma_f32_16x16x32_f16 v[80:83], v[148:151], v[216:219], v[80:83]
	v_mfma_f32_16x16x32_f16 v[76:79], v[156:159], v[216:219], v[76:79]
	v_mfma_f32_16x16x32_f16 v[120:123], v[160:163], v[176:179], v[120:123]
	v_mfma_f32_16x16x32_f16 v[116:119], v[168:171], v[176:179], v[116:119]
	v_mfma_f32_16x16x32_f16 v[104:107], v[160:163], v[184:187], v[104:107]
	v_mfma_f32_16x16x32_f16 v[100:103], v[168:171], v[184:187], v[100:103]
	v_mfma_f32_16x16x32_f16 v[88:91], v[160:163], v[192:195], v[88:91]
	v_mfma_f32_16x16x32_f16 v[84:87], v[168:171], v[192:195], v[84:87]
	v_mfma_f32_16x16x32_f16 v[72:75], v[160:163], v[212:215], v[72:75]
	v_mfma_f32_16x16x32_f16 v[68:71], v[168:171], v[212:215], v[68:71]
	v_mfma_f32_16x16x32_f16 v[120:123], v[164:167], v[180:183], v[120:123]
	v_mfma_f32_16x16x32_f16 v[116:119], v[172:175], v[180:183], v[116:119]
	v_mfma_f32_16x16x32_f16 v[104:107], v[164:167], v[188:191], v[104:107]
	v_mfma_f32_16x16x32_f16 v[100:103], v[172:175], v[188:191], v[100:103]
	v_mfma_f32_16x16x32_f16 v[88:91], v[164:167], v[208:211], v[88:91]
	v_mfma_f32_16x16x32_f16 v[84:87], v[172:175], v[208:211], v[84:87]
	v_mfma_f32_16x16x32_f16 v[72:75], v[164:167], v[216:219], v[72:75]
	v_mfma_f32_16x16x32_f16 v[68:71], v[172:175], v[216:219], v[68:71]
	s_barrier
; #define PG8_STAGE(bufoff, gbase, voff) do { _Pragma("unroll") for (int _i = 0; _i < 2; ++_i) \
;         __builtin_amdgcn_global_load_lds((const unsigned*)((const char*)(gbase) + (voff)[_i]), (LAS unsigned*)(lds + (bufoff) + ldsw + _i * 8192), 16, 0, 0); } while (0)
; #define PG8_LDA(dst, b, h) do { _Pragma("unroll") for (int m = 0; m < 4; ++m) _Pragma("unroll") for (int k = 0; k < 2; ++k) dst[m][k] = *(const LAS bf16x8*)(lds + PG8_SA(b, h) + aoff + m * 2048 + k * 1024); } while (0)
; #define PG8_WAIT_V(n) asm volatile("s_waitcnt vmcnt(" #n ")" ::: "memory")
; #define PG8_WAIT_L(n) asm volatile("s_waitcnt lgkmcnt(" #n ")" ::: "memory")
; #define PG8_BAR __builtin_amdgcn_s_barrier()
; #define PG8_SCHED __builtin_amdgcn_sched_barrier(0)
; template <class Epi, class Sched, bool FUSED = false, bool APERM = false>
; __device__ __forceinline__ void gemm_phase(int wid_s, LAS unsigned char* lds, const Gemm g, const Sched& S, const Epi& E) {
;     ...
;             PG8_LDA(At, 1, 1); PG8_STAGE(PG8_SB(1, 0), b3, voffB); PG8_STAGE(PG8_SB(1, 1), b3 + hstep, voffB); PG8_STAGE(PG8_SA(1, 0), a3, voffA);
;             PG8_WAIT_V(8); PG8_WAIT_L(0); PG8_BAR; PG8_MMA(1, 0, At, B0); PG8_MMA(1, 1, At, B1); PG8_BAR; PG8_SCHED;
;         }
;         if (wr == 0) PG8_BAR;
	s_add_i32 s38, s63, s48
	v_lshl_add_u64 v[200:201], v[200:201], 0, s[12:13]
	s_mov_b32 m0, s38
	ds_read_b128 v[176:179], v142 offset:49152
	ds_read_b128 v[180:183], v142 offset:50176
	ds_read_b128 v[184:187], v142 offset:51200
	ds_read_b128 v[188:191], v142 offset:52224
	ds_read_b128 v[192:195], v142 offset:53248
	ds_read_b128 v[208:211], v142 offset:54272
	ds_read_b128 v[212:215], v142 offset:55296
	ds_read_b128 v[216:219], v142 offset:56320
	global_load_lds_dwordx4 v[200:201], off
	s_add_i32 m0, s38, 0x2000
	s_add_u32 s36, s36, 0x158080
	v_lshl_add_u64 v[200:201], v[222:223], 0, s[12:13]
	s_addc_u32 s37, s37, 0
	s_add_i32 s38, s64, s48
	global_load_lds_dwordx4 v[200:201], off
	v_lshl_add_u64 v[200:201], s[36:37], 0, v[0:1]
	s_mov_b32 m0, s38
	s_nop 0
	global_load_lds_dwordx4 v[200:201], off
	v_lshl_add_u64 v[200:201], s[36:37], 0, v[132:133]
	s_add_i32 m0, s38, 0x2000
	s_nop 0
	global_load_lds_dwordx4 v[200:201], off
	v_lshl_add_u64 v[200:201], v[224:225], 0, s[12:13]
	s_mov_b32 m0, s54
	s_nop 0
	global_load_lds_dwordx4 v[200:201], off
	v_lshl_add_u64 v[200:201], v[226:227], 0, s[12:13]
	s_mov_b32 m0, s55
	s_nop 0
	global_load_lds_dwordx4 v[200:201], off
	s_waitcnt vmcnt(8)
	s_waitcnt lgkmcnt(0)
	s_barrier
	v_mfma_f32_16x16x32_f16 v[64:67], v[144:147], v[176:179], v[64:67]
	v_mfma_f32_16x16x32_f16 v[60:63], v[152:155], v[176:179], v[60:63]
	v_mfma_f32_16x16x32_f16 v[48:51], v[144:147], v[184:187], v[48:51]
	v_mfma_f32_16x16x32_f16 v[44:47], v[152:155], v[184:187], v[44:47]
	v_mfma_f32_16x16x32_f16 v[32:35], v[144:147], v[192:195], v[32:35]
	v_mfma_f32_16x16x32_f16 v[28:31], v[152:155], v[192:195], v[28:31]
	v_mfma_f32_16x16x32_f16 v[16:19], v[144:147], v[212:215], v[16:19]
	v_mfma_f32_16x16x32_f16 v[12:15], v[152:155], v[212:215], v[12:15]
	v_mfma_f32_16x16x32_f16 v[64:67], v[148:151], v[180:183], v[64:67]
	v_mfma_f32_16x16x32_f16 v[60:63], v[156:159], v[180:183], v[60:63]
	v_mfma_f32_16x16x32_f16 v[48:51], v[148:151], v[188:191], v[48:51]
	v_mfma_f32_16x16x32_f16 v[44:47], v[156:159], v[188:191], v[44:47]
	v_mfma_f32_16x16x32_f16 v[32:35], v[148:151], v[208:211], v[32:35]
	v_mfma_f32_16x16x32_f16 v[28:31], v[156:159], v[208:211], v[28:31]
	v_mfma_f32_16x16x32_f16 v[16:19], v[148:151], v[216:219], v[16:19]
	v_mfma_f32_16x16x32_f16 v[12:15], v[156:159], v[216:219], v[12:15]
	v_mfma_f32_16x16x32_f16 v[56:59], v[160:163], v[176:179], v[56:59]
	v_mfma_f32_16x16x32_f16 v[52:55], v[168:171], v[176:179], v[52:55]
	v_mfma_f32_16x16x32_f16 v[40:43], v[160:163], v[184:187], v[40:43]
	v_mfma_f32_16x16x32_f16 v[36:39], v[168:171], v[184:187], v[36:39]
	v_mfma_f32_16x16x32_f16 v[24:27], v[160:163], v[192:195], v[24:27]
	v_mfma_f32_16x16x32_f16 v[20:23], v[168:171], v[192:195], v[20:23]
	v_mfma_f32_16x16x32_f16 v[8:11], v[160:163], v[212:215], v[8:11]
	v_mfma_f32_16x16x32_f16 v[4:7], v[168:171], v[212:215], v[4:7]
	v_mfma_f32_16x16x32_f16 v[56:59], v[164:167], v[180:183], v[56:59]
	v_mfma_f32_16x16x32_f16 v[52:55], v[172:175], v[180:183], v[52:55]
	v_mfma_f32_16x16x32_f16 v[40:43], v[164:167], v[188:191], v[40:43]
	v_mfma_f32_16x16x32_f16 v[36:39], v[172:175], v[188:191], v[36:39]
	v_mfma_f32_16x16x32_f16 v[24:27], v[164:167], v[208:211], v[24:27]
	v_mfma_f32_16x16x32_f16 v[20:23], v[172:175], v[208:211], v[20:23]
	v_mfma_f32_16x16x32_f16 v[8:11], v[164:167], v[216:219], v[8:11]
	v_mfma_f32_16x16x32_f16 v[4:7], v[172:175], v[216:219], v[4:7]
	s_barrier
	s_add_i32 s62, s62, 2
	s_add_u32 s34, s34, 0x100
	s_addc_u32 s35, s35, 0
	s_cmpk_gt_u32 s62, 0x53
	s_cbranch_scc0 .LBB0_929
	s_and_b64 vcc, exec, s[26:27]
	s_cbranch_vccz .LBB0_932
	s_barrier
